# GEMM K-loops: per-phase s_setprio flips deleted, one static s_setprio 1 for waves 4-7 before each K-loop (reset to 0 after)
# speedup vs baseline: 1.0066x; 1.0016x over previous
; #define PG8_STAGE(bufoff, gbase, voff) do { _Pragma("unroll") for (int _i = 0; _i < 2; ++_i) \
;         __builtin_amdgcn_global_load_lds((const unsigned*)((const char*)(gbase) + (voff)[_i]), (LAS unsigned*)(lds + (bufoff) + ldsw + _i * 8192), 16, 0, 0); } while (0)
; #define PG8_LDA(dst, b, h) do { _Pragma("unroll") for (int m = 0; m < 4; ++m) _Pragma("unroll") for (int k = 0; k < 2; ++k) dst[m][k] = *(const LAS bf16x8*)(lds + PG8_SA(b, h) + aoff + m * 2048 + k * 1024); } while (0)
; #define PG8_LDB(dst, b, h) do { _Pragma("unroll") for (int n = 0; n < 2; ++n) _Pragma("unroll") for (int k = 0; k < 2; ++k) dst[n][k] = *(const LAS bf16x8*)(lds + PG8_SB(b, h) + boff + n * 2048 + k * 1024); } while (0)
; #define PG8_MMA(ai, bj, At, Bt) do { __builtin_amdgcn_s_setprio(1); _Pragma("unroll") for (int m = 0; m < 4; ++m) _Pragma("unroll") for (int n = 0; n < 2; ++n) _Pragma("unroll") for (int k = 0; k < 2; ++k) \
;         acc[ai][bj][m][n] = __builtin_amdgcn_mfma_f32_16x16x32_bf16(Bt[n][k], At[m][k], acc[ai][bj][m][n], 0, 0, 0); __builtin_amdgcn_s_setprio(0); } while (0)
; #define PG8_WAIT_V(n) asm volatile("s_waitcnt vmcnt(" #n ")" ::: "memory")
; #define PG8_WAIT_L(n) asm volatile("s_waitcnt lgkmcnt(" #n ")" ::: "memory")
; #define PG8_BAR __builtin_amdgcn_s_barrier()
; #define PG8_SCHED __builtin_amdgcn_sched_barrier(0)
; template <class Epi, bool ALIGN_EPI = true>
; __device__ __forceinline__ void gemm_phase(LAS unsigned char* lds, const Gemm g, const StaticOrder& S, const Epi& E) {
;     ...
;         for (int t = 0; t < nt; t += 2) {
;             const bool last = (t == nt - 2);
;             const char* a1 = cA + (size_t)(t + 1) * kstep;
;             const char* a2 = last ? nA : cA + (size_t)(t + 2) * kstep; const char* b2 = last ? nB : cB + (size_t)(t + 2) * kstep;
;             const char* a3 = a2 + kstep; const char* b3 = b2 + kstep;
;             PG8_LDB(B0, 0, 0); PG8_LDB(B1, 0, 1); PG8_SCHED; PG8_LDA(At, 0, 0); PG8_STAGE(PG8_SA(1, 1), a1 + hsA, voffA);
;             PG8_WAIT_V(8); PG8_WAIT_L(0); PG8_BAR; PG8_MMA(0, 0, At, B0); PG8_MMA(0, 1, At, B1); PG8_BAR; PG8_SCHED;
;             PG8_LDA(At, 0, 1); PG8_STAGE(PG8_SB(0, 0), b2, voffB); PG8_STAGE(PG8_SB(0, 1), b2 + hsB, voffB); PG8_STAGE(PG8_SA(0, 0), a2, voffA);
;             PG8_WAIT_V(8); PG8_WAIT_L(0); PG8_BAR; PG8_MMA(1, 0, At, B0); PG8_MMA(1, 1, At, B1); PG8_BAR; PG8_SCHED;
.LBB0_228:
	s_mov_b32 s84, 0
	s_mov_b64 vcc, 0x100
	v_mov_b64_e32 v[146:147], v[144:145]
	v_mov_b64_e32 v[148:149], v[142:143]
	s_mov_b64 s[86:87], 0x100
	v_readfirstlane_b32 s11, v0
	s_lshr_b32 s11, s11, 6
	s_cmp_ge_u32 s11, 4
	s_cbranch_scc0 .Lsp_skip_229
	s_setprio 1
.Lsp_skip_229:
.LBB0_229:
	s_add_i32 s11, s84, 2
	s_add_u32 s80, s6, vcc_lo
	s_addc_u32 s81, s7, vcc_hi
	s_add_u32 s97, s82, vcc_lo
	s_addc_u32 s22, s83, vcc_hi
	s_cmp_eq_u32 s72, s84
	s_cselect_b32 s85, s9, s81
	s_cselect_b32 s84, s8, s80
	s_cselect_b32 s81, s89, s22
	s_cselect_b32 s80, s88, s97
	s_add_i32 s22, 0, 0x14000
	v_add_u32_e32 v164, s91, v150
	v_add_u32_e32 v168, s22, v150
	ds_read_b128 v[152:155], v164
	ds_read_b128 v[156:159], v164 offset:1024
	ds_read_b128 v[160:163], v164 offset:2048
	ds_read_b128 v[164:167], v164 offset:3072
	ds_read_b128 v[176:179], v168
	ds_read_b128 v[180:183], v168 offset:1024
	ds_read_b128 v[184:187], v168 offset:2048
	ds_read_b128 v[188:191], v168 offset:3072
	v_lshl_add_u64 v[168:169], s[6:7], 0, v[148:149]
	s_add_i32 m0, s25, 0xc000
	ds_read_b128 v[192:195], v151
	ds_read_b128 v[196:199], v151 offset:1024
	ds_read_b128 v[200:203], v151 offset:2048
	ds_read_b128 v[222:225], v151 offset:3072
	ds_read_b128 v[226:229], v151 offset:4096
	ds_read_b128 v[230:233], v151 offset:5120
	ds_read_b128 v[234:237], v151 offset:6144
	ds_read_b128 v[238:241], v151 offset:7168
	global_load_lds_dwordx4 v[168:169], off
	v_lshl_add_u64 v[168:169], s[6:7], 0, v[146:147]
	s_add_i32 m0, s25, 0xe000
	s_nop 0
	global_load_lds_dwordx4 v[168:169], off
	s_waitcnt vmcnt(8)
	s_waitcnt lgkmcnt(0)
	s_barrier
	s_waitcnt lgkmcnt(0)
	v_mfma_f32_16x16x32_bf16 v[134:137], v[152:155], v[192:195], v[134:137]
	v_mfma_f32_16x16x32_bf16 v[130:133], v[160:163], v[192:195], v[130:133]
	v_mfma_f32_16x16x32_bf16 v[118:121], v[152:155], v[200:203], v[118:121]
	v_mfma_f32_16x16x32_bf16 v[114:117], v[160:163], v[200:203], v[114:117]
	v_mfma_f32_16x16x32_bf16 v[102:105], v[152:155], v[226:229], v[102:105]
	v_mfma_f32_16x16x32_bf16 v[98:101], v[160:163], v[226:229], v[98:101]
	v_mfma_f32_16x16x32_bf16 v[86:89], v[152:155], v[234:237], v[86:89]
	v_mfma_f32_16x16x32_bf16 v[82:85], v[160:163], v[234:237], v[82:85]
	v_mfma_f32_16x16x32_bf16 v[134:137], v[156:159], v[196:199], v[134:137]
	v_mfma_f32_16x16x32_bf16 v[130:133], v[164:167], v[196:199], v[130:133]
	v_mfma_f32_16x16x32_bf16 v[118:121], v[156:159], v[222:225], v[118:121]
	v_mfma_f32_16x16x32_bf16 v[114:117], v[164:167], v[222:225], v[114:117]
	v_mfma_f32_16x16x32_bf16 v[102:105], v[156:159], v[230:233], v[102:105]
	v_mfma_f32_16x16x32_bf16 v[98:101], v[164:167], v[230:233], v[98:101]
	v_mfma_f32_16x16x32_bf16 v[86:89], v[156:159], v[238:241], v[86:89]
	v_mfma_f32_16x16x32_bf16 v[82:85], v[164:167], v[238:241], v[82:85]
	v_mfma_f32_16x16x32_bf16 v[126:129], v[176:179], v[192:195], v[126:129]
	v_mfma_f32_16x16x32_bf16 v[122:125], v[184:187], v[192:195], v[122:125]
	v_mfma_f32_16x16x32_bf16 v[110:113], v[176:179], v[200:203], v[110:113]
	v_mfma_f32_16x16x32_bf16 v[106:109], v[184:187], v[200:203], v[106:109]
	v_mfma_f32_16x16x32_bf16 v[94:97], v[176:179], v[226:229], v[94:97]
	v_mfma_f32_16x16x32_bf16 v[90:93], v[184:187], v[226:229], v[90:93]
	v_mfma_f32_16x16x32_bf16 v[78:81], v[176:179], v[234:237], v[78:81]
	v_mfma_f32_16x16x32_bf16 v[74:77], v[184:187], v[234:237], v[74:77]
	v_mfma_f32_16x16x32_bf16 v[126:129], v[180:183], v[196:199], v[126:129]
	v_mfma_f32_16x16x32_bf16 v[122:125], v[188:191], v[196:199], v[122:125]
	v_mfma_f32_16x16x32_bf16 v[110:113], v[180:183], v[222:225], v[110:113]
	v_mfma_f32_16x16x32_bf16 v[106:109], v[188:191], v[222:225], v[106:109]
	v_mfma_f32_16x16x32_bf16 v[94:97], v[180:183], v[230:233], v[94:97]
	v_mfma_f32_16x16x32_bf16 v[90:93], v[188:191], v[230:233], v[90:93]
	v_mfma_f32_16x16x32_bf16 v[78:81], v[180:183], v[238:241], v[78:81]
	v_mfma_f32_16x16x32_bf16 v[74:77], v[188:191], v[238:241], v[74:77]
	s_barrier
	s_add_i32 s97, s91, s3
	v_lshl_add_u64 v[168:169], s[80:81], 0, v[2:3]
	s_mov_b32 m0, s97
	ds_read_b128 v[192:195], v151 offset:16384
	ds_read_b128 v[196:199], v151 offset:17408
	ds_read_b128 v[200:203], v151 offset:18432
	ds_read_b128 v[222:225], v151 offset:19456
	ds_read_b128 v[226:229], v151 offset:20480
	ds_read_b128 v[230:233], v151 offset:21504
	ds_read_b128 v[234:237], v151 offset:22528
	ds_read_b128 v[238:241], v151 offset:23552
	global_load_lds_dwordx4 v[168:169], off
	s_add_i32 m0, s97, 0x2000
	v_lshl_add_u64 v[172:173], s[80:81], 0, v[4:5]
	s_add_u32 s80, s80, s96
	s_addc_u32 s81, s81, 0
	s_add_i32 s22, s22, s3
	global_load_lds_dwordx4 v[172:173], off
	v_lshl_add_u64 v[244:245], s[80:81], 0, v[2:3]
	s_mov_b32 m0, s22
	v_lshl_add_u64 v[246:247], s[80:81], 0, v[4:5]
	global_load_lds_dwordx4 v[244:245], off
	s_add_i32 m0, s22, 0x2000
	v_lshl_add_u64 v[248:249], s[84:85], 0, v[140:141]
	global_load_lds_dwordx4 v[246:247], off
	s_mov_b32 m0, s25
	v_lshl_add_u64 v[250:251], s[84:85], 0, v[138:139]
	global_load_lds_dwordx4 v[248:249], off
	s_mov_b32 m0, s26
	s_nop 0
	global_load_lds_dwordx4 v[250:251], off
	s_waitcnt vmcnt(8)
	s_waitcnt lgkmcnt(0)
	s_barrier
; #define PG8_STAGE(bufoff, gbase, voff) do { _Pragma("unroll") for (int _i = 0; _i < 2; ++_i) \
;         __builtin_amdgcn_global_load_lds((const unsigned*)((const char*)(gbase) + (voff)[_i]), (LAS unsigned*)(lds + (bufoff) + ldsw + _i * 8192), 16, 0, 0); } while (0)
; #define PG8_LDA(dst, b, h) do { _Pragma("unroll") for (int m = 0; m < 4; ++m) _Pragma("unroll") for (int k = 0; k < 2; ++k) dst[m][k] = *(const LAS bf16x8*)(lds + PG8_SA(b, h) + aoff + m * 2048 + k * 1024); } while (0)
; #define PG8_LDB(dst, b, h) do { _Pragma("unroll") for (int n = 0; n < 2; ++n) _Pragma("unroll") for (int k = 0; k < 2; ++k) dst[n][k] = *(const LAS bf16x8*)(lds + PG8_SB(b, h) + boff + n * 2048 + k * 1024); } while (0)
; #define PG8_MMA(ai, bj, At, Bt) do { __builtin_amdgcn_s_setprio(1); _Pragma("unroll") for (int m = 0; m < 4; ++m) _Pragma("unroll") for (int n = 0; n < 2; ++n) _Pragma("unroll") for (int k = 0; k < 2; ++k) \
;         acc[ai][bj][m][n] = __builtin_amdgcn_mfma_f32_16x16x32_bf16(Bt[n][k], At[m][k], acc[ai][bj][m][n], 0, 0, 0); __builtin_amdgcn_s_setprio(0); } while (0)
; #define PG8_WAIT_V(n) asm volatile("s_waitcnt vmcnt(" #n ")" ::: "memory")
; #define PG8_WAIT_L(n) asm volatile("s_waitcnt lgkmcnt(" #n ")" ::: "memory")
; #define PG8_BAR __builtin_amdgcn_s_barrier()
; #define PG8_SCHED __builtin_amdgcn_sched_barrier(0)
; template <class Epi, bool ALIGN_EPI = true>
; __device__ __forceinline__ void gemm_phase(LAS unsigned char* lds, const Gemm g, const StaticOrder& S, const Epi& E) {
;     ...
;             PG8_WAIT_V(8); PG8_WAIT_L(0); PG8_BAR; PG8_MMA(1, 0, At, B0); PG8_MMA(1, 1, At, B1); PG8_BAR; PG8_SCHED;
;             PG8_LDB(B0, 1, 0); PG8_LDB(B1, 1, 1); PG8_SCHED; PG8_LDA(At, 1, 0); PG8_STAGE(PG8_SA(0, 1), a2 + hsA, voffA);
;             PG8_WAIT_V(8); PG8_WAIT_L(0); PG8_BAR; PG8_MMA(0, 0, At, B0); PG8_MMA(0, 1, At, B1); PG8_BAR; PG8_SCHED;
	s_waitcnt lgkmcnt(0)
	v_mfma_f32_16x16x32_bf16 v[70:73], v[152:155], v[192:195], v[70:73]
	v_mfma_f32_16x16x32_bf16 v[66:69], v[160:163], v[192:195], v[66:69]
	v_mfma_f32_16x16x32_bf16 v[54:57], v[152:155], v[200:203], v[54:57]
	v_mfma_f32_16x16x32_bf16 v[50:53], v[160:163], v[200:203], v[50:53]
	v_mfma_f32_16x16x32_bf16 v[38:41], v[152:155], v[226:229], v[38:41]
	v_mfma_f32_16x16x32_bf16 v[34:37], v[160:163], v[226:229], v[34:37]
	v_mfma_f32_16x16x32_bf16 v[22:25], v[152:155], v[234:237], v[22:25]
	v_mfma_f32_16x16x32_bf16 v[18:21], v[160:163], v[234:237], v[18:21]
	v_mfma_f32_16x16x32_bf16 v[70:73], v[156:159], v[196:199], v[70:73]
	v_mfma_f32_16x16x32_bf16 v[66:69], v[164:167], v[196:199], v[66:69]
	v_mfma_f32_16x16x32_bf16 v[54:57], v[156:159], v[222:225], v[54:57]
	v_mfma_f32_16x16x32_bf16 v[50:53], v[164:167], v[222:225], v[50:53]
	v_mfma_f32_16x16x32_bf16 v[38:41], v[156:159], v[230:233], v[38:41]
	v_mfma_f32_16x16x32_bf16 v[34:37], v[164:167], v[230:233], v[34:37]
	v_mfma_f32_16x16x32_bf16 v[22:25], v[156:159], v[238:241], v[22:25]
	v_mfma_f32_16x16x32_bf16 v[18:21], v[164:167], v[238:241], v[18:21]
	v_mfma_f32_16x16x32_bf16 v[62:65], v[176:179], v[192:195], v[62:65]
	v_mfma_f32_16x16x32_bf16 v[58:61], v[184:187], v[192:195], v[58:61]
	v_mfma_f32_16x16x32_bf16 v[46:49], v[176:179], v[200:203], v[46:49]
	v_mfma_f32_16x16x32_bf16 v[42:45], v[184:187], v[200:203], v[42:45]
	v_mfma_f32_16x16x32_bf16 v[30:33], v[176:179], v[226:229], v[30:33]
	v_mfma_f32_16x16x32_bf16 v[26:29], v[184:187], v[226:229], v[26:29]
	v_mfma_f32_16x16x32_bf16 v[14:17], v[176:179], v[234:237], v[14:17]
	v_mfma_f32_16x16x32_bf16 v[10:13], v[184:187], v[234:237], v[10:13]
	v_mfma_f32_16x16x32_bf16 v[62:65], v[180:183], v[196:199], v[62:65]
	v_mfma_f32_16x16x32_bf16 v[58:61], v[188:191], v[196:199], v[58:61]
	v_mfma_f32_16x16x32_bf16 v[46:49], v[180:183], v[222:225], v[46:49]
	v_mfma_f32_16x16x32_bf16 v[42:45], v[188:191], v[222:225], v[42:45]
	v_mfma_f32_16x16x32_bf16 v[30:33], v[180:183], v[230:233], v[30:33]
	v_mfma_f32_16x16x32_bf16 v[26:29], v[188:191], v[230:233], v[26:29]
	v_mfma_f32_16x16x32_bf16 v[14:17], v[180:183], v[238:241], v[14:17]
	v_mfma_f32_16x16x32_bf16 v[10:13], v[188:191], v[238:241], v[10:13]
	s_barrier
	s_add_i32 s22, 0, 0x18000
	s_add_i32 s97, 0, 0x1c000
	v_add_u32_e32 v164, s22, v150
	v_add_u32_e32 v188, s97, v150
	ds_read_b128 v[152:155], v164
	ds_read_b128 v[156:159], v164 offset:1024
	ds_read_b128 v[160:163], v164 offset:2048
	ds_read_b128 v[164:167], v164 offset:3072
	ds_read_b128 v[176:179], v188
	ds_read_b128 v[180:183], v188 offset:1024
	ds_read_b128 v[184:187], v188 offset:2048
	ds_read_b128 v[188:191], v188 offset:3072
	s_add_u32 s80, s84, s14
	s_addc_u32 s81, s85, 0
	s_mov_b32 m0, s36
	v_lshl_add_u64 v[204:205], s[80:81], 0, v[140:141]
	ds_read_b128 v[192:195], v151 offset:32768
	ds_read_b128 v[196:199], v151 offset:33792
	ds_read_b128 v[200:203], v151 offset:34816
	ds_read_b128 v[222:225], v151 offset:35840
	ds_read_b128 v[226:229], v151 offset:36864
	ds_read_b128 v[230:233], v151 offset:37888
	ds_read_b128 v[234:237], v151 offset:38912
	ds_read_b128 v[238:241], v151 offset:39936
	global_load_lds_dwordx4 v[204:205], off
	v_lshl_add_u64 v[204:205], s[80:81], 0, v[138:139]
	s_mov_b32 m0, s69
	s_nop 0
	global_load_lds_dwordx4 v[204:205], off
	s_waitcnt vmcnt(8)
	s_waitcnt lgkmcnt(0)
	s_barrier
	s_waitcnt lgkmcnt(0)
	v_mfma_f32_16x16x32_bf16 v[134:137], v[152:155], v[192:195], v[134:137]
	v_mfma_f32_16x16x32_bf16 v[130:133], v[160:163], v[192:195], v[130:133]
	v_mfma_f32_16x16x32_bf16 v[118:121], v[152:155], v[200:203], v[118:121]
	v_mfma_f32_16x16x32_bf16 v[114:117], v[160:163], v[200:203], v[114:117]
	v_mfma_f32_16x16x32_bf16 v[102:105], v[152:155], v[226:229], v[102:105]
	v_mfma_f32_16x16x32_bf16 v[98:101], v[160:163], v[226:229], v[98:101]
	v_mfma_f32_16x16x32_bf16 v[86:89], v[152:155], v[234:237], v[86:89]
	v_mfma_f32_16x16x32_bf16 v[82:85], v[160:163], v[234:237], v[82:85]
	v_mfma_f32_16x16x32_bf16 v[134:137], v[156:159], v[196:199], v[134:137]
	v_mfma_f32_16x16x32_bf16 v[130:133], v[164:167], v[196:199], v[130:133]
	v_mfma_f32_16x16x32_bf16 v[118:121], v[156:159], v[222:225], v[118:121]
	v_mfma_f32_16x16x32_bf16 v[114:117], v[164:167], v[222:225], v[114:117]
	v_mfma_f32_16x16x32_bf16 v[102:105], v[156:159], v[230:233], v[102:105]
	v_mfma_f32_16x16x32_bf16 v[98:101], v[164:167], v[230:233], v[98:101]
	v_mfma_f32_16x16x32_bf16 v[86:89], v[156:159], v[238:241], v[86:89]
	v_mfma_f32_16x16x32_bf16 v[82:85], v[164:167], v[238:241], v[82:85]
	v_mfma_f32_16x16x32_bf16 v[126:129], v[176:179], v[192:195], v[126:129]
	v_mfma_f32_16x16x32_bf16 v[122:125], v[184:187], v[192:195], v[122:125]
	v_mfma_f32_16x16x32_bf16 v[110:113], v[176:179], v[200:203], v[110:113]
	v_mfma_f32_16x16x32_bf16 v[106:109], v[184:187], v[200:203], v[106:109]
	v_mfma_f32_16x16x32_bf16 v[94:97], v[176:179], v[226:229], v[94:97]
	v_mfma_f32_16x16x32_bf16 v[90:93], v[184:187], v[226:229], v[90:93]
	v_mfma_f32_16x16x32_bf16 v[78:81], v[176:179], v[234:237], v[78:81]
	v_mfma_f32_16x16x32_bf16 v[74:77], v[184:187], v[234:237], v[74:77]
	v_mfma_f32_16x16x32_bf16 v[126:129], v[180:183], v[196:199], v[126:129]
	v_mfma_f32_16x16x32_bf16 v[122:125], v[188:191], v[196:199], v[122:125]
	v_mfma_f32_16x16x32_bf16 v[110:113], v[180:183], v[222:225], v[110:113]
	v_mfma_f32_16x16x32_bf16 v[106:109], v[188:191], v[222:225], v[106:109]
	v_mfma_f32_16x16x32_bf16 v[94:97], v[180:183], v[230:233], v[94:97]
	v_mfma_f32_16x16x32_bf16 v[90:93], v[188:191], v[230:233], v[90:93]
	v_mfma_f32_16x16x32_bf16 v[78:81], v[180:183], v[238:241], v[78:81]
	v_mfma_f32_16x16x32_bf16 v[74:77], v[188:191], v[238:241], v[74:77]
	s_barrier
; #define PG8_STAGE(bufoff, gbase, voff) do { _Pragma("unroll") for (int _i = 0; _i < 2; ++_i) \
;         __builtin_amdgcn_global_load_lds((const unsigned*)((const char*)(gbase) + (voff)[_i]), (LAS unsigned*)(lds + (bufoff) + ldsw + _i * 8192), 16, 0, 0); } while (0)
; #define PG8_LDA(dst, b, h) do { _Pragma("unroll") for (int m = 0; m < 4; ++m) _Pragma("unroll") for (int k = 0; k < 2; ++k) dst[m][k] = *(const LAS bf16x8*)(lds + PG8_SA(b, h) + aoff + m * 2048 + k * 1024); } while (0)
; #define PG8_MMA(ai, bj, At, Bt) do { __builtin_amdgcn_s_setprio(1); _Pragma("unroll") for (int m = 0; m < 4; ++m) _Pragma("unroll") for (int n = 0; n < 2; ++n) _Pragma("unroll") for (int k = 0; k < 2; ++k) \
;         acc[ai][bj][m][n] = __builtin_amdgcn_mfma_f32_16x16x32_bf16(Bt[n][k], At[m][k], acc[ai][bj][m][n], 0, 0, 0); __builtin_amdgcn_s_setprio(0); } while (0)
; #define PG8_WAIT_V(n) asm volatile("s_waitcnt vmcnt(" #n ")" ::: "memory")
; #define PG8_WAIT_L(n) asm volatile("s_waitcnt lgkmcnt(" #n ")" ::: "memory")
; #define PG8_BAR __builtin_amdgcn_s_barrier()
; #define PG8_SCHED __builtin_amdgcn_sched_barrier(0)
; template <class Epi, bool ALIGN_EPI = true>
; __device__ __forceinline__ void gemm_phase(LAS unsigned char* lds, const Gemm g, const StaticOrder& S, const Epi& E) {
;     ...
;             PG8_LDA(At, 1, 1); PG8_STAGE(PG8_SB(1, 0), b3, voffB); PG8_STAGE(PG8_SB(1, 1), b3 + hsB, voffB); PG8_STAGE(PG8_SA(1, 0), a3, voffA);
;             PG8_WAIT_V(8); PG8_WAIT_L(0); PG8_BAR; PG8_MMA(1, 0, At, B0); PG8_MMA(1, 1, At, B1); PG8_BAR; PG8_SCHED;
;         }
;         if constexpr (ALIGN_EPI) { if (wr == 0) PG8_BAR; }
;         if constexpr (!Epi::AFTER_DRAIN) E.fast(acc, cur, wr, wc, fr, fq, rsc);
;         if (!has_next) break;
	s_add_i32 s22, s22, s3
	v_lshl_add_u64 v[168:169], v[168:169], 0, s[70:71]
	s_mov_b32 m0, s22
	ds_read_b128 v[192:195], v151 offset:49152
	ds_read_b128 v[196:199], v151 offset:50176
	ds_read_b128 v[200:203], v151 offset:51200
	ds_read_b128 v[222:225], v151 offset:52224
	ds_read_b128 v[226:229], v151 offset:53248
	ds_read_b128 v[230:233], v151 offset:54272
	ds_read_b128 v[234:237], v151 offset:55296
	ds_read_b128 v[238:241], v151 offset:56320
	global_load_lds_dwordx4 v[168:169], off
	v_lshl_add_u64 v[168:169], v[172:173], 0, s[70:71]
	s_add_i32 m0, s22, 0x2000
	s_add_i32 s22, s97, s3
	global_load_lds_dwordx4 v[168:169], off
	v_lshl_add_u64 v[168:169], v[244:245], 0, s[70:71]
	s_mov_b32 m0, s22
	s_nop 0
	global_load_lds_dwordx4 v[168:169], off
	v_lshl_add_u64 v[168:169], v[246:247], 0, s[70:71]
	s_add_i32 m0, s22, 0x2000
	s_nop 0
	global_load_lds_dwordx4 v[168:169], off
	v_lshl_add_u64 v[168:169], v[248:249], 0, s[70:71]
	s_mov_b32 m0, s73
	s_nop 0
	global_load_lds_dwordx4 v[168:169], off
	v_lshl_add_u64 v[168:169], v[250:251], 0, s[70:71]
	s_mov_b32 m0, s74
	s_nop 0
	global_load_lds_dwordx4 v[168:169], off
	s_waitcnt vmcnt(8)
	s_waitcnt lgkmcnt(0)
	s_barrier
	s_waitcnt lgkmcnt(0)
	v_mfma_f32_16x16x32_bf16 v[70:73], v[152:155], v[192:195], v[70:73]
	v_mfma_f32_16x16x32_bf16 v[66:69], v[160:163], v[192:195], v[66:69]
	v_mfma_f32_16x16x32_bf16 v[54:57], v[152:155], v[200:203], v[54:57]
	v_mfma_f32_16x16x32_bf16 v[50:53], v[160:163], v[200:203], v[50:53]
	v_mfma_f32_16x16x32_bf16 v[38:41], v[152:155], v[226:229], v[38:41]
	v_mfma_f32_16x16x32_bf16 v[34:37], v[160:163], v[226:229], v[34:37]
	v_mfma_f32_16x16x32_bf16 v[22:25], v[152:155], v[234:237], v[22:25]
	v_mfma_f32_16x16x32_bf16 v[18:21], v[160:163], v[234:237], v[18:21]
	v_mfma_f32_16x16x32_bf16 v[70:73], v[156:159], v[196:199], v[70:73]
	v_mfma_f32_16x16x32_bf16 v[66:69], v[164:167], v[196:199], v[66:69]
	v_mfma_f32_16x16x32_bf16 v[54:57], v[156:159], v[222:225], v[54:57]
	v_mfma_f32_16x16x32_bf16 v[50:53], v[164:167], v[222:225], v[50:53]
	v_mfma_f32_16x16x32_bf16 v[38:41], v[156:159], v[230:233], v[38:41]
	v_mfma_f32_16x16x32_bf16 v[34:37], v[164:167], v[230:233], v[34:37]
	v_mfma_f32_16x16x32_bf16 v[22:25], v[156:159], v[238:241], v[22:25]
	v_mfma_f32_16x16x32_bf16 v[18:21], v[164:167], v[238:241], v[18:21]
	v_mfma_f32_16x16x32_bf16 v[62:65], v[176:179], v[192:195], v[62:65]
	v_mfma_f32_16x16x32_bf16 v[58:61], v[184:187], v[192:195], v[58:61]
	v_mfma_f32_16x16x32_bf16 v[46:49], v[176:179], v[200:203], v[46:49]
	v_mfma_f32_16x16x32_bf16 v[42:45], v[184:187], v[200:203], v[42:45]
	v_mfma_f32_16x16x32_bf16 v[30:33], v[176:179], v[226:229], v[30:33]
	v_mfma_f32_16x16x32_bf16 v[26:29], v[184:187], v[226:229], v[26:29]
	v_mfma_f32_16x16x32_bf16 v[14:17], v[176:179], v[234:237], v[14:17]
	v_mfma_f32_16x16x32_bf16 v[10:13], v[184:187], v[234:237], v[10:13]
	v_mfma_f32_16x16x32_bf16 v[62:65], v[180:183], v[196:199], v[62:65]
	v_mfma_f32_16x16x32_bf16 v[58:61], v[188:191], v[196:199], v[58:61]
	v_mfma_f32_16x16x32_bf16 v[46:49], v[180:183], v[222:225], v[46:49]
	v_mfma_f32_16x16x32_bf16 v[42:45], v[188:191], v[222:225], v[42:45]
	v_mfma_f32_16x16x32_bf16 v[30:33], v[180:183], v[230:233], v[30:33]
	v_mfma_f32_16x16x32_bf16 v[26:29], v[188:191], v[230:233], v[26:29]
	v_mfma_f32_16x16x32_bf16 v[14:17], v[180:183], v[238:241], v[14:17]
	v_mfma_f32_16x16x32_bf16 v[10:13], v[188:191], v[238:241], v[10:13]
	s_barrier
	s_add_u32 vcc_lo, vcc_lo, 0x100
	s_addc_u32 vcc_hi, vcc_hi, 0
	v_lshl_add_u64 v[148:149], v[148:149], 0, s[86:87]
	v_lshl_add_u64 v[146:147], v[146:147], 0, s[86:87]
	s_cmp_ge_u32 s11, s95
	s_mov_b32 s84, s11
	s_cbranch_scc0 .LBB0_229
	s_setprio 0
	v_readlane_b32 s80, v255, 0
	v_readlane_b32 s81, v255, 1
	s_and_b64 vcc, exec, s[80:81]
	s_cbranch_vccz .LBB0_232
	s_barrier

; #define PG8_STAGE(bufoff, gbase, voff) do { _Pragma("unroll") for (int _i = 0; _i < 2; ++_i) \
;         __builtin_amdgcn_global_load_lds((const unsigned*)((const char*)(gbase) + (voff)[_i]), (LAS unsigned*)(lds + (bufoff) + ldsw + _i * 8192), 16, 0, 0); } while (0)
; #define PG8_LDA(dst, b, h) do { _Pragma("unroll") for (int m = 0; m < 4; ++m) _Pragma("unroll") for (int k = 0; k < 2; ++k) dst[m][k] = *(const LAS bf16x8*)(lds + PG8_SA(b, h) + aoff + m * 2048 + k * 1024); } while (0)
; #define PG8_LDB(dst, b, h) do { _Pragma("unroll") for (int n = 0; n < 2; ++n) _Pragma("unroll") for (int k = 0; k < 2; ++k) dst[n][k] = *(const LAS bf16x8*)(lds + PG8_SB(b, h) + boff + n * 2048 + k * 1024); } while (0)
; #define PG8_MMA(ai, bj, At, Bt) do { __builtin_amdgcn_s_setprio(1); _Pragma("unroll") for (int m = 0; m < 4; ++m) _Pragma("unroll") for (int n = 0; n < 2; ++n) _Pragma("unroll") for (int k = 0; k < 2; ++k) \
;         acc[ai][bj][m][n] = __builtin_amdgcn_mfma_f32_16x16x32_bf16(Bt[n][k], At[m][k], acc[ai][bj][m][n], 0, 0, 0); __builtin_amdgcn_s_setprio(0); } while (0)
; #define PG8_WAIT_V(n) asm volatile("s_waitcnt vmcnt(" #n ")" ::: "memory")
; #define PG8_WAIT_L(n) asm volatile("s_waitcnt lgkmcnt(" #n ")" ::: "memory")
; #define PG8_BAR __builtin_amdgcn_s_barrier()
; template <class Epi, bool ALIGN_EPI = true>
; __device__ __forceinline__ void gemm_phase(LAS unsigned char* lds, const Gemm g, const StaticOrder& S, const Epi& E) {
;     ...
;         for (int t = 0; t < nt; t += 2) {
;             const bool last = (t == nt - 2);
;             const char* a1 = cA + (size_t)(t + 1) * kstep;
;             const char* a2 = last ? nA : cA + (size_t)(t + 2) * kstep; const char* b2 = last ? nB : cB + (size_t)(t + 2) * kstep;
;             const char* a3 = a2 + kstep; const char* b3 = b2 + kstep;
;             PG8_LDB(B0, 0, 0); PG8_LDB(B1, 0, 1); PG8_SCHED; PG8_LDA(At, 0, 0); PG8_STAGE(PG8_SA(1, 1), a1 + hsA, voffA);
;             PG8_WAIT_V(8); PG8_WAIT_L(0); PG8_BAR; PG8_MMA(0, 0, At, B0); PG8_MMA(0, 1, At, B1); PG8_BAR; PG8_SCHED;
;     ...
;         for (int a = 0; a < 2; ++a)
; #pragma unroll
;             for (int b = 0; b < 2; ++b)
; #pragma unroll
;                 for (int m = 0; m < 4; ++m)
; #pragma unroll
;                     for (int n = 0; n < 2; ++n) acc[a][b][m][n] = (f32x4){0.f, 0.f, 0.f, 0.f};
;         cur = nxt; cA = nA; cB = nB; ++ui;
.LBB0_258:
	s_add_u32 s0, s8, 0x80
	s_addc_u32 s1, s9, 0
	s_add_u32 s8, s6, 0x100
	v_mov_b32_e32 v10, 0
	s_addc_u32 s9, s7, 0
	s_mov_b32 s6, 0
	v_mov_b32_e32 v11, v10
	v_mov_b32_e32 v12, v10
	v_mov_b32_e32 v13, v10
	v_mov_b32_e32 v14, v10
	v_mov_b32_e32 v15, v10
	v_mov_b32_e32 v16, v10
	v_mov_b32_e32 v17, v10
	v_mov_b32_e32 v26, v10
	v_mov_b32_e32 v27, v10
	v_mov_b32_e32 v28, v10
	v_mov_b32_e32 v29, v10
	v_mov_b32_e32 v30, v10
	v_mov_b32_e32 v31, v10
	v_mov_b32_e32 v32, v10
	v_mov_b32_e32 v33, v10
	v_mov_b32_e32 v42, v10
	v_mov_b32_e32 v43, v10
	v_mov_b32_e32 v44, v10
	v_mov_b32_e32 v45, v10
	v_mov_b32_e32 v46, v10
	v_mov_b32_e32 v47, v10
	v_mov_b32_e32 v48, v10
	v_mov_b32_e32 v49, v10
	v_mov_b32_e32 v62, v10
	v_mov_b32_e32 v63, v10
	v_mov_b32_e32 v64, v10
	v_mov_b32_e32 v65, v10
	v_mov_b32_e32 v78, v10
	v_mov_b32_e32 v79, v10
	v_mov_b32_e32 v80, v10
	v_mov_b32_e32 v81, v10
	v_mov_b32_e32 v18, v10
	v_mov_b32_e32 v19, v10
	v_mov_b32_e32 v20, v10
	v_mov_b32_e32 v21, v10
	v_mov_b32_e32 v22, v10
	v_mov_b32_e32 v23, v10
	v_mov_b32_e32 v24, v10
	v_mov_b32_e32 v25, v10
	v_mov_b32_e32 v34, v10
	v_mov_b32_e32 v35, v10
	v_mov_b32_e32 v36, v10
	v_mov_b32_e32 v37, v10
	v_mov_b32_e32 v38, v10
	v_mov_b32_e32 v39, v10
	v_mov_b32_e32 v40, v10
	v_mov_b32_e32 v41, v10
	v_mov_b32_e32 v50, v10
	v_mov_b32_e32 v51, v10
	v_mov_b32_e32 v52, v10
	v_mov_b32_e32 v53, v10
	v_mov_b32_e32 v54, v10
	v_mov_b32_e32 v55, v10
	v_mov_b32_e32 v56, v10
	v_mov_b32_e32 v57, v10
	v_mov_b32_e32 v82, v10
	v_mov_b32_e32 v83, v10
	v_mov_b32_e32 v84, v10
	v_mov_b32_e32 v85, v10
	v_mov_b32_e32 v86, v10
	v_mov_b32_e32 v87, v10
	v_mov_b32_e32 v88, v10
	v_mov_b32_e32 v89, v10
	v_mov_b32_e32 v106, v10
	v_mov_b32_e32 v107, v10
	v_mov_b32_e32 v108, v10
	v_mov_b32_e32 v109, v10
	v_mov_b32_e32 v110, v10
	v_mov_b32_e32 v111, v10
	v_mov_b32_e32 v112, v10
	v_mov_b32_e32 v113, v10
	v_mov_b32_e32 v122, v10
	v_mov_b32_e32 v123, v10
	v_mov_b32_e32 v124, v10
	v_mov_b32_e32 v125, v10
	v_mov_b32_e32 v126, v10
	v_mov_b32_e32 v127, v10
	v_mov_b32_e32 v128, v10
	v_mov_b32_e32 v129, v10
	v_mov_b32_e32 v138, v10
	v_mov_b32_e32 v139, v10
	v_mov_b32_e32 v140, v10
	v_mov_b32_e32 v141, v10
	v_mov_b32_e32 v142, v10
	v_mov_b32_e32 v143, v10
	v_mov_b32_e32 v144, v10
	v_mov_b32_e32 v145, v10
	v_mov_b32_e32 v154, v10
	v_mov_b32_e32 v155, v10
	v_mov_b32_e32 v156, v10
	v_mov_b32_e32 v157, v10
	v_mov_b32_e32 v158, v10
	v_mov_b32_e32 v159, v10
	v_mov_b32_e32 v160, v10
	v_mov_b32_e32 v161, v10
	v_mov_b32_e32 v114, v10
	v_mov_b32_e32 v115, v10
	v_mov_b32_e32 v116, v10
	v_mov_b32_e32 v117, v10
	v_mov_b32_e32 v118, v10
	v_mov_b32_e32 v119, v10
	v_mov_b32_e32 v120, v10
	v_mov_b32_e32 v121, v10
	v_mov_b32_e32 v130, v10
	v_mov_b32_e32 v131, v10
	v_mov_b32_e32 v132, v10
	v_mov_b32_e32 v133, v10
	v_mov_b32_e32 v134, v10
	v_mov_b32_e32 v135, v10
	v_mov_b32_e32 v136, v10
	v_mov_b32_e32 v137, v10
	v_mov_b32_e32 v146, v10
	v_mov_b32_e32 v147, v10
	v_mov_b32_e32 v148, v10
	v_mov_b32_e32 v149, v10
	v_mov_b32_e32 v150, v10
	v_mov_b32_e32 v151, v10
	v_mov_b32_e32 v152, v10
	v_mov_b32_e32 v153, v10
	v_mov_b32_e32 v162, v10
	v_mov_b32_e32 v163, v10
	v_mov_b32_e32 v164, v10
	v_mov_b32_e32 v165, v10
	v_mov_b32_e32 v166, v10
	v_mov_b32_e32 v167, v10
	v_mov_b32_e32 v168, v10
	v_mov_b32_e32 v169, v10
	v_readfirstlane_b32 s74, v0
	s_lshr_b32 s74, s74, 6
	s_cmp_ge_u32 s74, 4
	s_cbranch_scc0 .Lsp_skip_259
	s_setprio 1
.Lsp_skip_259:
.LBB0_259:
	s_add_i32 s74, s6, 2
	s_add_u32 s75, s0, 0x80
	s_addc_u32 s7, s1, 0
	s_cmp_eq_u32 s72, s6
	s_cselect_b32 s7, s89, s7
	s_cselect_b32 s6, s88, s75
	s_cselect_b32 s81, s23, s9
	s_cselect_b32 s80, s22, s8
	s_add_i32 s75, 0, 0x14000
	v_add_u32_e32 v74, s91, v221
	v_add_u32_e32 v102, s75, v221
	ds_read_b128 v[58:61], v74
	ds_read_b128 v[66:69], v74 offset:1024
	ds_read_b128 v[70:73], v74 offset:2048
	ds_read_b128 v[74:77], v74 offset:3072
	ds_read_b128 v[90:93], v102
	ds_read_b128 v[94:97], v102 offset:1024
	ds_read_b128 v[98:101], v102 offset:2048
	ds_read_b128 v[102:105], v102 offset:3072
	v_lshl_add_u64 v[172:173], s[0:1], 0, v[180:181]
	s_add_i32 m0, s24, 0xc000
	ds_read_b128 v[184:187], v222
	ds_read_b128 v[188:191], v222 offset:1024
	ds_read_b128 v[192:195], v222 offset:2048
	ds_read_b128 v[196:199], v222 offset:3072
	ds_read_b128 v[200:203], v222 offset:4096
	ds_read_b128 v[224:227], v222 offset:5120
	ds_read_b128 v[228:231], v222 offset:6144
	ds_read_b128 v[232:235], v222 offset:7168
	global_load_lds_dwordx4 v[172:173], off
	v_lshl_add_u64 v[172:173], s[0:1], 0, v[182:183]
	s_add_i32 m0, s24, 0xe000
	s_nop 0
	global_load_lds_dwordx4 v[172:173], off
	s_waitcnt vmcnt(8)
	s_waitcnt lgkmcnt(0)
	s_barrier
; #define PG8_STAGE(bufoff, gbase, voff) do { _Pragma("unroll") for (int _i = 0; _i < 2; ++_i) \
;         __builtin_amdgcn_global_load_lds((const unsigned*)((const char*)(gbase) + (voff)[_i]), (LAS unsigned*)(lds + (bufoff) + ldsw + _i * 8192), 16, 0, 0); } while (0)
; #define PG8_LDA(dst, b, h) do { _Pragma("unroll") for (int m = 0; m < 4; ++m) _Pragma("unroll") for (int k = 0; k < 2; ++k) dst[m][k] = *(const LAS bf16x8*)(lds + PG8_SA(b, h) + aoff + m * 2048 + k * 1024); } while (0)
; #define PG8_MMA(ai, bj, At, Bt) do { __builtin_amdgcn_s_setprio(1); _Pragma("unroll") for (int m = 0; m < 4; ++m) _Pragma("unroll") for (int n = 0; n < 2; ++n) _Pragma("unroll") for (int k = 0; k < 2; ++k) \
;         acc[ai][bj][m][n] = __builtin_amdgcn_mfma_f32_16x16x32_bf16(Bt[n][k], At[m][k], acc[ai][bj][m][n], 0, 0, 0); __builtin_amdgcn_s_setprio(0); } while (0)
; #define PG8_WAIT_V(n) asm volatile("s_waitcnt vmcnt(" #n ")" ::: "memory")
; #define PG8_WAIT_L(n) asm volatile("s_waitcnt lgkmcnt(" #n ")" ::: "memory")
; #define PG8_BAR __builtin_amdgcn_s_barrier()
; #define PG8_SCHED __builtin_amdgcn_sched_barrier(0)
; template <class Epi, bool ALIGN_EPI = true>
; __device__ __forceinline__ void gemm_phase(LAS unsigned char* lds, const Gemm g, const StaticOrder& S, const Epi& E) {
;     ...
;             PG8_WAIT_V(8); PG8_WAIT_L(0); PG8_BAR; PG8_MMA(0, 0, At, B0); PG8_MMA(0, 1, At, B1); PG8_BAR; PG8_SCHED;
;             PG8_LDA(At, 0, 1); PG8_STAGE(PG8_SB(0, 0), b2, voffB); PG8_STAGE(PG8_SB(0, 1), b2 + hsB, voffB); PG8_STAGE(PG8_SA(0, 0), a2, voffA);
;             PG8_WAIT_V(8); PG8_WAIT_L(0); PG8_BAR; PG8_MMA(1, 0, At, B0); PG8_MMA(1, 1, At, B1); PG8_BAR; PG8_SCHED;
	s_waitcnt lgkmcnt(0)
	v_mfma_f32_16x16x32_bf16 v[166:169], v[58:61], v[184:187], v[166:169]
	v_mfma_f32_16x16x32_bf16 v[162:165], v[70:73], v[184:187], v[162:165]
	v_mfma_f32_16x16x32_bf16 v[150:153], v[58:61], v[192:195], v[150:153]
	v_mfma_f32_16x16x32_bf16 v[146:149], v[70:73], v[192:195], v[146:149]
	v_mfma_f32_16x16x32_bf16 v[134:137], v[58:61], v[200:203], v[134:137]
	v_mfma_f32_16x16x32_bf16 v[130:133], v[70:73], v[200:203], v[130:133]
	v_mfma_f32_16x16x32_bf16 v[118:121], v[58:61], v[228:231], v[118:121]
	v_mfma_f32_16x16x32_bf16 v[114:117], v[70:73], v[228:231], v[114:117]
	v_mfma_f32_16x16x32_bf16 v[166:169], v[66:69], v[188:191], v[166:169]
	v_mfma_f32_16x16x32_bf16 v[162:165], v[74:77], v[188:191], v[162:165]
	v_mfma_f32_16x16x32_bf16 v[150:153], v[66:69], v[196:199], v[150:153]
	v_mfma_f32_16x16x32_bf16 v[146:149], v[74:77], v[196:199], v[146:149]
	v_mfma_f32_16x16x32_bf16 v[134:137], v[66:69], v[224:227], v[134:137]
	v_mfma_f32_16x16x32_bf16 v[130:133], v[74:77], v[224:227], v[130:133]
	v_mfma_f32_16x16x32_bf16 v[118:121], v[66:69], v[232:235], v[118:121]
	v_mfma_f32_16x16x32_bf16 v[114:117], v[74:77], v[232:235], v[114:117]
	v_mfma_f32_16x16x32_bf16 v[158:161], v[90:93], v[184:187], v[158:161]
	v_mfma_f32_16x16x32_bf16 v[154:157], v[98:101], v[184:187], v[154:157]
	v_mfma_f32_16x16x32_bf16 v[142:145], v[90:93], v[192:195], v[142:145]
	v_mfma_f32_16x16x32_bf16 v[138:141], v[98:101], v[192:195], v[138:141]
	v_mfma_f32_16x16x32_bf16 v[126:129], v[90:93], v[200:203], v[126:129]
	v_mfma_f32_16x16x32_bf16 v[122:125], v[98:101], v[200:203], v[122:125]
	v_mfma_f32_16x16x32_bf16 v[110:113], v[90:93], v[228:231], v[110:113]
	v_mfma_f32_16x16x32_bf16 v[106:109], v[98:101], v[228:231], v[106:109]
	v_mfma_f32_16x16x32_bf16 v[158:161], v[94:97], v[188:191], v[158:161]
	v_mfma_f32_16x16x32_bf16 v[154:157], v[102:105], v[188:191], v[154:157]
	v_mfma_f32_16x16x32_bf16 v[142:145], v[94:97], v[196:199], v[142:145]
	v_mfma_f32_16x16x32_bf16 v[138:141], v[102:105], v[196:199], v[138:141]
	v_mfma_f32_16x16x32_bf16 v[126:129], v[94:97], v[224:227], v[126:129]
	v_mfma_f32_16x16x32_bf16 v[122:125], v[102:105], v[224:227], v[122:125]
	v_mfma_f32_16x16x32_bf16 v[110:113], v[94:97], v[232:235], v[110:113]
	v_mfma_f32_16x16x32_bf16 v[106:109], v[102:105], v[232:235], v[106:109]
	s_barrier
	s_add_i32 s78, s91, s11
	v_lshl_add_u64 v[172:173], s[80:81], 0, v[2:3]
	s_mov_b32 m0, s78
	ds_read_b128 v[184:187], v222 offset:16384
	ds_read_b128 v[188:191], v222 offset:17408
	ds_read_b128 v[192:195], v222 offset:18432
	ds_read_b128 v[196:199], v222 offset:19456
	ds_read_b128 v[200:203], v222 offset:20480
	ds_read_b128 v[224:227], v222 offset:21504
	ds_read_b128 v[228:231], v222 offset:22528
	ds_read_b128 v[232:235], v222 offset:23552
	global_load_lds_dwordx4 v[172:173], off
	s_add_i32 m0, s78, 0x2000
	v_lshl_add_u64 v[236:237], s[80:81], 0, v[178:179]
	s_add_u32 s80, s80, s96
	s_addc_u32 s81, s81, 0
	s_add_i32 s75, s75, s11
	global_load_lds_dwordx4 v[236:237], off
	v_lshl_add_u64 v[238:239], s[80:81], 0, v[2:3]
	s_mov_b32 m0, s75
	v_lshl_add_u64 v[240:241], s[80:81], 0, v[178:179]
	global_load_lds_dwordx4 v[238:239], off
	s_add_i32 m0, s75, 0x2000
	v_lshl_add_u64 v[244:245], s[6:7], 0, v[4:5]
	global_load_lds_dwordx4 v[240:241], off
	s_mov_b32 m0, s24
	v_lshl_add_u64 v[246:247], s[6:7], 0, v[176:177]
	global_load_lds_dwordx4 v[244:245], off
	s_mov_b32 m0, s25
	s_nop 0
	global_load_lds_dwordx4 v[246:247], off
	s_waitcnt vmcnt(8)
	s_waitcnt lgkmcnt(0)
	s_barrier
	s_waitcnt lgkmcnt(0)
	v_mfma_f32_16x16x32_bf16 v[86:89], v[58:61], v[184:187], v[86:89]
	v_mfma_f32_16x16x32_bf16 v[82:85], v[70:73], v[184:187], v[82:85]
	v_mfma_f32_16x16x32_bf16 v[54:57], v[58:61], v[192:195], v[54:57]
	v_mfma_f32_16x16x32_bf16 v[50:53], v[70:73], v[192:195], v[50:53]
	v_mfma_f32_16x16x32_bf16 v[38:41], v[58:61], v[200:203], v[38:41]
	v_mfma_f32_16x16x32_bf16 v[34:37], v[70:73], v[200:203], v[34:37]
	v_mfma_f32_16x16x32_bf16 v[22:25], v[58:61], v[228:231], v[22:25]
	v_mfma_f32_16x16x32_bf16 v[18:21], v[70:73], v[228:231], v[18:21]
	v_mfma_f32_16x16x32_bf16 v[86:89], v[66:69], v[188:191], v[86:89]
	v_mfma_f32_16x16x32_bf16 v[82:85], v[74:77], v[188:191], v[82:85]
	v_mfma_f32_16x16x32_bf16 v[54:57], v[66:69], v[196:199], v[54:57]
	v_mfma_f32_16x16x32_bf16 v[50:53], v[74:77], v[196:199], v[50:53]
	v_mfma_f32_16x16x32_bf16 v[38:41], v[66:69], v[224:227], v[38:41]
	v_mfma_f32_16x16x32_bf16 v[34:37], v[74:77], v[224:227], v[34:37]
	v_mfma_f32_16x16x32_bf16 v[22:25], v[66:69], v[232:235], v[22:25]
	v_mfma_f32_16x16x32_bf16 v[18:21], v[74:77], v[232:235], v[18:21]
	v_mfma_f32_16x16x32_bf16 v[62:65], v[98:101], v[184:187], v[62:65]
	v_mfma_f32_16x16x32_bf16 v[46:49], v[90:93], v[192:195], v[46:49]
	v_mfma_f32_16x16x32_bf16 v[42:45], v[98:101], v[192:195], v[42:45]
	v_mfma_f32_16x16x32_bf16 v[30:33], v[90:93], v[200:203], v[30:33]
	v_mfma_f32_16x16x32_bf16 v[26:29], v[98:101], v[200:203], v[26:29]
	v_mfma_f32_16x16x32_bf16 v[14:17], v[90:93], v[228:231], v[14:17]
	v_mfma_f32_16x16x32_bf16 v[10:13], v[98:101], v[228:231], v[10:13]
	v_mfma_f32_16x16x32_bf16 v[58:61], v[90:93], v[184:187], v[78:81]
	v_mfma_f32_16x16x32_bf16 v[62:65], v[102:105], v[188:191], v[62:65]
	v_mfma_f32_16x16x32_bf16 v[46:49], v[94:97], v[196:199], v[46:49]
	v_mfma_f32_16x16x32_bf16 v[42:45], v[102:105], v[196:199], v[42:45]
	v_mfma_f32_16x16x32_bf16 v[30:33], v[94:97], v[224:227], v[30:33]
	v_mfma_f32_16x16x32_bf16 v[26:29], v[102:105], v[224:227], v[26:29]
	v_mfma_f32_16x16x32_bf16 v[14:17], v[94:97], v[232:235], v[14:17]
	v_mfma_f32_16x16x32_bf16 v[10:13], v[102:105], v[232:235], v[10:13]
	v_mfma_f32_16x16x32_bf16 v[58:61], v[94:97], v[188:191], v[58:61]
	s_barrier
; #define PG8_STAGE(bufoff, gbase, voff) do { _Pragma("unroll") for (int _i = 0; _i < 2; ++_i) \
;         __builtin_amdgcn_global_load_lds((const unsigned*)((const char*)(gbase) + (voff)[_i]), (LAS unsigned*)(lds + (bufoff) + ldsw + _i * 8192), 16, 0, 0); } while (0)
; #define PG8_LDA(dst, b, h) do { _Pragma("unroll") for (int m = 0; m < 4; ++m) _Pragma("unroll") for (int k = 0; k < 2; ++k) dst[m][k] = *(const LAS bf16x8*)(lds + PG8_SA(b, h) + aoff + m * 2048 + k * 1024); } while (0)
; #define PG8_LDB(dst, b, h) do { _Pragma("unroll") for (int n = 0; n < 2; ++n) _Pragma("unroll") for (int k = 0; k < 2; ++k) dst[n][k] = *(const LAS bf16x8*)(lds + PG8_SB(b, h) + boff + n * 2048 + k * 1024); } while (0)
; #define PG8_MMA(ai, bj, At, Bt) do { __builtin_amdgcn_s_setprio(1); _Pragma("unroll") for (int m = 0; m < 4; ++m) _Pragma("unroll") for (int n = 0; n < 2; ++n) _Pragma("unroll") for (int k = 0; k < 2; ++k) \
;         acc[ai][bj][m][n] = __builtin_amdgcn_mfma_f32_16x16x32_bf16(Bt[n][k], At[m][k], acc[ai][bj][m][n], 0, 0, 0); __builtin_amdgcn_s_setprio(0); } while (0)
; #define PG8_WAIT_V(n) asm volatile("s_waitcnt vmcnt(" #n ")" ::: "memory")
; #define PG8_WAIT_L(n) asm volatile("s_waitcnt lgkmcnt(" #n ")" ::: "memory")
; #define PG8_BAR __builtin_amdgcn_s_barrier()
; #define PG8_SCHED __builtin_amdgcn_sched_barrier(0)
; template <class Epi, bool ALIGN_EPI = true>
; __device__ __forceinline__ void gemm_phase(LAS unsigned char* lds, const Gemm g, const StaticOrder& S, const Epi& E) {
;     ...
;             PG8_LDB(B0, 1, 0); PG8_LDB(B1, 1, 1); PG8_SCHED; PG8_LDA(At, 1, 0); PG8_STAGE(PG8_SA(0, 1), a2 + hsA, voffA);
;             PG8_WAIT_V(8); PG8_WAIT_L(0); PG8_BAR; PG8_MMA(0, 0, At, B0); PG8_MMA(0, 1, At, B1); PG8_BAR; PG8_SCHED;
	s_add_i32 s75, 0, 0x18000
	s_add_i32 s78, 0, 0x1c000
	v_add_u32_e32 v78, s75, v221
	v_add_u32_e32 v102, s78, v221
	ds_read_b128 v[66:69], v78
	ds_read_b128 v[70:73], v78 offset:1024
	ds_read_b128 v[74:77], v78 offset:2048
	ds_read_b128 v[78:81], v78 offset:3072
	ds_read_b128 v[90:93], v102
	ds_read_b128 v[94:97], v102 offset:1024
	ds_read_b128 v[98:101], v102 offset:2048
	ds_read_b128 v[102:105], v102 offset:3072
	s_add_u32 s6, s6, s14
	s_addc_u32 s7, s7, 0
	s_mov_b32 m0, s26
	v_lshl_add_u64 v[248:249], s[6:7], 0, v[4:5]
	ds_read_b128 v[184:187], v222 offset:32768
	ds_read_b128 v[188:191], v222 offset:33792
	ds_read_b128 v[192:195], v222 offset:34816
	ds_read_b128 v[196:199], v222 offset:35840
	ds_read_b128 v[200:203], v222 offset:36864
	ds_read_b128 v[224:227], v222 offset:37888
	ds_read_b128 v[228:231], v222 offset:38912
	ds_read_b128 v[232:235], v222 offset:39936
	global_load_lds_dwordx4 v[248:249], off
	v_lshl_add_u64 v[248:249], s[6:7], 0, v[176:177]
	s_mov_b32 m0, s36
	s_nop 0
	global_load_lds_dwordx4 v[248:249], off
	s_waitcnt vmcnt(8)
	s_waitcnt lgkmcnt(0)
	s_barrier
	s_waitcnt lgkmcnt(0)
	v_mfma_f32_16x16x32_bf16 v[166:169], v[66:69], v[184:187], v[166:169]
	v_mfma_f32_16x16x32_bf16 v[162:165], v[74:77], v[184:187], v[162:165]
	v_mfma_f32_16x16x32_bf16 v[150:153], v[66:69], v[192:195], v[150:153]
	v_mfma_f32_16x16x32_bf16 v[146:149], v[74:77], v[192:195], v[146:149]
	v_mfma_f32_16x16x32_bf16 v[134:137], v[66:69], v[200:203], v[134:137]
	v_mfma_f32_16x16x32_bf16 v[130:133], v[74:77], v[200:203], v[130:133]
	v_mfma_f32_16x16x32_bf16 v[118:121], v[66:69], v[228:231], v[118:121]
	v_mfma_f32_16x16x32_bf16 v[114:117], v[74:77], v[228:231], v[114:117]
	v_mfma_f32_16x16x32_bf16 v[166:169], v[70:73], v[188:191], v[166:169]
	v_mfma_f32_16x16x32_bf16 v[162:165], v[78:81], v[188:191], v[162:165]
	v_mfma_f32_16x16x32_bf16 v[150:153], v[70:73], v[196:199], v[150:153]
	v_mfma_f32_16x16x32_bf16 v[146:149], v[78:81], v[196:199], v[146:149]
	v_mfma_f32_16x16x32_bf16 v[134:137], v[70:73], v[224:227], v[134:137]
	v_mfma_f32_16x16x32_bf16 v[130:133], v[78:81], v[224:227], v[130:133]
	v_mfma_f32_16x16x32_bf16 v[118:121], v[70:73], v[232:235], v[118:121]
	v_mfma_f32_16x16x32_bf16 v[114:117], v[78:81], v[232:235], v[114:117]
	v_mfma_f32_16x16x32_bf16 v[158:161], v[90:93], v[184:187], v[158:161]
	v_mfma_f32_16x16x32_bf16 v[154:157], v[98:101], v[184:187], v[154:157]
	v_mfma_f32_16x16x32_bf16 v[142:145], v[90:93], v[192:195], v[142:145]
	v_mfma_f32_16x16x32_bf16 v[138:141], v[98:101], v[192:195], v[138:141]
	v_mfma_f32_16x16x32_bf16 v[126:129], v[90:93], v[200:203], v[126:129]
	v_mfma_f32_16x16x32_bf16 v[122:125], v[98:101], v[200:203], v[122:125]
	v_mfma_f32_16x16x32_bf16 v[110:113], v[90:93], v[228:231], v[110:113]
	v_mfma_f32_16x16x32_bf16 v[106:109], v[98:101], v[228:231], v[106:109]
	v_mfma_f32_16x16x32_bf16 v[158:161], v[94:97], v[188:191], v[158:161]
	v_mfma_f32_16x16x32_bf16 v[154:157], v[102:105], v[188:191], v[154:157]
	v_mfma_f32_16x16x32_bf16 v[142:145], v[94:97], v[196:199], v[142:145]
	v_mfma_f32_16x16x32_bf16 v[138:141], v[102:105], v[196:199], v[138:141]
	v_mfma_f32_16x16x32_bf16 v[126:129], v[94:97], v[224:227], v[126:129]
	v_mfma_f32_16x16x32_bf16 v[122:125], v[102:105], v[224:227], v[122:125]
	v_mfma_f32_16x16x32_bf16 v[110:113], v[94:97], v[232:235], v[110:113]
	v_mfma_f32_16x16x32_bf16 v[106:109], v[102:105], v[232:235], v[106:109]
	s_barrier
; #define PG8_STAGE(bufoff, gbase, voff) do { _Pragma("unroll") for (int _i = 0; _i < 2; ++_i) \
;         __builtin_amdgcn_global_load_lds((const unsigned*)((const char*)(gbase) + (voff)[_i]), (LAS unsigned*)(lds + (bufoff) + ldsw + _i * 8192), 16, 0, 0); } while (0)
; #define PG8_LDA(dst, b, h) do { _Pragma("unroll") for (int m = 0; m < 4; ++m) _Pragma("unroll") for (int k = 0; k < 2; ++k) dst[m][k] = *(const LAS bf16x8*)(lds + PG8_SA(b, h) + aoff + m * 2048 + k * 1024); } while (0)
; #define PG8_MMA(ai, bj, At, Bt) do { __builtin_amdgcn_s_setprio(1); _Pragma("unroll") for (int m = 0; m < 4; ++m) _Pragma("unroll") for (int n = 0; n < 2; ++n) _Pragma("unroll") for (int k = 0; k < 2; ++k) \
;         acc[ai][bj][m][n] = __builtin_amdgcn_mfma_f32_16x16x32_bf16(Bt[n][k], At[m][k], acc[ai][bj][m][n], 0, 0, 0); __builtin_amdgcn_s_setprio(0); } while (0)
; #define PG8_WAIT_V(n) asm volatile("s_waitcnt vmcnt(" #n ")" ::: "memory")
; #define PG8_WAIT_L(n) asm volatile("s_waitcnt lgkmcnt(" #n ")" ::: "memory")
; #define PG8_BAR __builtin_amdgcn_s_barrier()
; #define PG8_SCHED __builtin_amdgcn_sched_barrier(0)
; template <class Epi, bool ALIGN_EPI = true>
; __device__ __forceinline__ void gemm_phase(LAS unsigned char* lds, const Gemm g, const StaticOrder& S, const Epi& E) {
;     ...
;             PG8_LDA(At, 1, 1); PG8_STAGE(PG8_SB(1, 0), b3, voffB); PG8_STAGE(PG8_SB(1, 1), b3 + hsB, voffB); PG8_STAGE(PG8_SA(1, 0), a3, voffA);
;             PG8_WAIT_V(8); PG8_WAIT_L(0); PG8_BAR; PG8_MMA(1, 0, At, B0); PG8_MMA(1, 1, At, B1); PG8_BAR; PG8_SCHED;
;         }
;         if constexpr (ALIGN_EPI) { if (wr == 0) PG8_BAR; }
;         if constexpr (!Epi::AFTER_DRAIN) E.fast(acc, cur, wr, wc, fr, fq, rsc);
;         if (!has_next) break;
	s_add_i32 s6, s75, s11
	v_lshl_add_u64 v[172:173], v[172:173], 0, s[70:71]
	s_mov_b32 m0, s6
	ds_read_b128 v[184:187], v222 offset:49152
	ds_read_b128 v[188:191], v222 offset:50176
	ds_read_b128 v[192:195], v222 offset:51200
	ds_read_b128 v[196:199], v222 offset:52224
	ds_read_b128 v[200:203], v222 offset:53248
	ds_read_b128 v[224:227], v222 offset:54272
	ds_read_b128 v[228:231], v222 offset:55296
	ds_read_b128 v[232:235], v222 offset:56320
	global_load_lds_dwordx4 v[172:173], off
	v_lshl_add_u64 v[172:173], v[236:237], 0, s[70:71]
	s_add_i32 m0, s6, 0x2000
	s_add_i32 s6, s78, s11
	global_load_lds_dwordx4 v[172:173], off
	v_lshl_add_u64 v[172:173], v[238:239], 0, s[70:71]
	s_mov_b32 m0, s6
	s_nop 0
	global_load_lds_dwordx4 v[172:173], off
	v_lshl_add_u64 v[172:173], v[240:241], 0, s[70:71]
	s_add_i32 m0, s6, 0x2000
	s_nop 0
	global_load_lds_dwordx4 v[172:173], off
	v_lshl_add_u64 v[172:173], v[244:245], 0, s[70:71]
	s_mov_b32 m0, s69
	s_nop 0
	global_load_lds_dwordx4 v[172:173], off
	v_lshl_add_u64 v[172:173], v[246:247], 0, s[70:71]
	s_mov_b32 m0, s73
	s_nop 0
	global_load_lds_dwordx4 v[172:173], off
	s_waitcnt vmcnt(8)
	s_waitcnt lgkmcnt(0)
	s_barrier
	s_waitcnt lgkmcnt(0)
	v_mfma_f32_16x16x32_bf16 v[86:89], v[66:69], v[184:187], v[86:89]
	v_mfma_f32_16x16x32_bf16 v[82:85], v[74:77], v[184:187], v[82:85]
	v_mfma_f32_16x16x32_bf16 v[54:57], v[66:69], v[192:195], v[54:57]
	v_mfma_f32_16x16x32_bf16 v[50:53], v[74:77], v[192:195], v[50:53]
	v_mfma_f32_16x16x32_bf16 v[38:41], v[66:69], v[200:203], v[38:41]
	v_mfma_f32_16x16x32_bf16 v[34:37], v[74:77], v[200:203], v[34:37]
	v_mfma_f32_16x16x32_bf16 v[22:25], v[66:69], v[228:231], v[22:25]
	v_mfma_f32_16x16x32_bf16 v[18:21], v[74:77], v[228:231], v[18:21]
	v_mfma_f32_16x16x32_bf16 v[86:89], v[70:73], v[188:191], v[86:89]
	v_mfma_f32_16x16x32_bf16 v[82:85], v[78:81], v[188:191], v[82:85]
	v_mfma_f32_16x16x32_bf16 v[54:57], v[70:73], v[196:199], v[54:57]
	v_mfma_f32_16x16x32_bf16 v[50:53], v[78:81], v[196:199], v[50:53]
	v_mfma_f32_16x16x32_bf16 v[38:41], v[70:73], v[224:227], v[38:41]
	v_mfma_f32_16x16x32_bf16 v[34:37], v[78:81], v[224:227], v[34:37]
	v_mfma_f32_16x16x32_bf16 v[22:25], v[70:73], v[232:235], v[22:25]
	v_mfma_f32_16x16x32_bf16 v[18:21], v[78:81], v[232:235], v[18:21]
	v_mfma_f32_16x16x32_bf16 v[58:61], v[90:93], v[184:187], v[58:61]
	v_mfma_f32_16x16x32_bf16 v[78:81], v[94:97], v[188:191], v[58:61]
	v_mfma_f32_16x16x32_bf16 v[58:61], v[98:101], v[184:187], v[62:65]
	v_mfma_f32_16x16x32_bf16 v[46:49], v[90:93], v[192:195], v[46:49]
	v_mfma_f32_16x16x32_bf16 v[42:45], v[98:101], v[192:195], v[42:45]
	v_mfma_f32_16x16x32_bf16 v[30:33], v[90:93], v[200:203], v[30:33]
	v_mfma_f32_16x16x32_bf16 v[26:29], v[98:101], v[200:203], v[26:29]
	v_mfma_f32_16x16x32_bf16 v[14:17], v[90:93], v[228:231], v[14:17]
	v_mfma_f32_16x16x32_bf16 v[10:13], v[98:101], v[228:231], v[10:13]
	v_mfma_f32_16x16x32_bf16 v[62:65], v[102:105], v[188:191], v[58:61]
	v_mfma_f32_16x16x32_bf16 v[46:49], v[94:97], v[196:199], v[46:49]
	v_mfma_f32_16x16x32_bf16 v[42:45], v[102:105], v[196:199], v[42:45]
	v_mfma_f32_16x16x32_bf16 v[30:33], v[94:97], v[224:227], v[30:33]
	v_mfma_f32_16x16x32_bf16 v[26:29], v[102:105], v[224:227], v[26:29]
	v_mfma_f32_16x16x32_bf16 v[14:17], v[94:97], v[232:235], v[14:17]
	v_mfma_f32_16x16x32_bf16 v[10:13], v[102:105], v[232:235], v[10:13]
	s_barrier
	s_add_u32 s0, s0, 0x100
	s_addc_u32 s1, s1, 0
	s_add_u32 s8, s8, 0x100
	s_addc_u32 s9, s9, 0
	s_cmp_ge_u32 s74, s95
	s_mov_b32 s6, s74
	s_cbranch_scc0 .LBB0_259
	s_setprio 0
	v_readlane_b32 s0, v255, 0
	v_readlane_b32 s1, v255, 1
	s_and_b64 vcc, exec, s[0:1]
	s_cbranch_vccz .LBB0_262
	s_barrier

; #define PG8_STAGE(bufoff, gbase, voff) do { _Pragma("unroll") for (int _i = 0; _i < 2; ++_i) \
;         __builtin_amdgcn_global_load_lds((const unsigned*)((const char*)(gbase) + (voff)[_i]), (LAS unsigned*)(lds + (bufoff) + ldsw + _i * 8192), 16, 0, 0); } while (0)
; #define PG8_LDA(dst, b, h) do { _Pragma("unroll") for (int m = 0; m < 4; ++m) _Pragma("unroll") for (int k = 0; k < 2; ++k) dst[m][k] = *(const LAS bf16x8*)(lds + PG8_SA(b, h) + aoff + m * 2048 + k * 1024); } while (0)
; #define PG8_LDB(dst, b, h) do { _Pragma("unroll") for (int n = 0; n < 2; ++n) _Pragma("unroll") for (int k = 0; k < 2; ++k) dst[n][k] = *(const LAS bf16x8*)(lds + PG8_SB(b, h) + boff + n * 2048 + k * 1024); } while (0)
; #define PG8_SCHED __builtin_amdgcn_sched_barrier(0)
; template <class Epi, bool ALIGN_EPI = true>
; __device__ __forceinline__ void gemm_phase(LAS unsigned char* lds, const Gemm g, const StaticOrder& S, const Epi& E) {
;     ...
;         const bool has_next = S.next(ui + 1, nxt);
;         const char* nA = has_next ? (const char*)g.A + (size_t)nxt.pm * tsA : cA; const char* nB = has_next ? (const char*)g.Bt + (size_t)nxt.pn * tsB : cB;
;         for (int t = 0; t < nt; t += 2) {
;             const bool last = (t == nt - 2);
;             const char* a1 = cA + (size_t)(t + 1) * kstep;
;             const char* a2 = last ? nA : cA + (size_t)(t + 2) * kstep; const char* b2 = last ? nB : cB + (size_t)(t + 2) * kstep;
;             const char* a3 = a2 + kstep; const char* b3 = b2 + kstep;
;             PG8_LDB(B0, 0, 0); PG8_LDB(B1, 0, 1); PG8_SCHED; PG8_LDA(At, 0, 0); PG8_STAGE(PG8_SA(1, 1), a1 + hsA, voffA);
;     ...
; #pragma unroll
;         for (int a = 0; a < 2; ++a)
; #pragma unroll
;             for (int b = 0; b < 2; ++b)
; #pragma unroll
;                 for (int m = 0; m < 4; ++m)
; #pragma unroll
;                     for (int n = 0; n < 2; ++n) acc[a][b][m][n] = (f32x4){0.f, 0.f, 0.f, 0.f};
.LBB0_296:
	s_add_u32 s0, s86, 0x80
	s_addc_u32 s1, s87, 0
	s_add_u32 s86, s82, 0x100
	v_mov_b32_e32 v10, 0
	s_addc_u32 s87, s83, 0
	s_mov_b32 s82, 0
	v_mov_b32_e32 v11, v10
	v_mov_b32_e32 v12, v10
	v_mov_b32_e32 v13, v10
	v_mov_b32_e32 v14, v10
	v_mov_b32_e32 v15, v10
	v_mov_b32_e32 v16, v10
	v_mov_b32_e32 v17, v10
	v_mov_b32_e32 v26, v10
	v_mov_b32_e32 v27, v10
	v_mov_b32_e32 v28, v10
	v_mov_b32_e32 v29, v10
	v_mov_b32_e32 v30, v10
	v_mov_b32_e32 v31, v10
	v_mov_b32_e32 v32, v10
	v_mov_b32_e32 v33, v10
	v_mov_b32_e32 v42, v10
	v_mov_b32_e32 v43, v10
	v_mov_b32_e32 v44, v10
	v_mov_b32_e32 v45, v10
	v_mov_b32_e32 v46, v10
	v_mov_b32_e32 v47, v10
	v_mov_b32_e32 v48, v10
	v_mov_b32_e32 v49, v10
	v_mov_b32_e32 v58, v10
	v_mov_b32_e32 v59, v10
	v_mov_b32_e32 v60, v10
	v_mov_b32_e32 v61, v10
	v_mov_b32_e32 v62, v10
	v_mov_b32_e32 v63, v10
	v_mov_b32_e32 v64, v10
	v_mov_b32_e32 v65, v10
	v_mov_b32_e32 v18, v10
	v_mov_b32_e32 v19, v10
	v_mov_b32_e32 v20, v10
	v_mov_b32_e32 v21, v10
	v_mov_b32_e32 v22, v10
	v_mov_b32_e32 v23, v10
	v_mov_b32_e32 v24, v10
	v_mov_b32_e32 v25, v10
	v_mov_b32_e32 v34, v10
	v_mov_b32_e32 v35, v10
	v_mov_b32_e32 v36, v10
	v_mov_b32_e32 v37, v10
	v_mov_b32_e32 v38, v10
	v_mov_b32_e32 v39, v10
	v_mov_b32_e32 v40, v10
	v_mov_b32_e32 v41, v10
	v_mov_b32_e32 v50, v10
	v_mov_b32_e32 v51, v10
	v_mov_b32_e32 v52, v10
	v_mov_b32_e32 v53, v10
	v_mov_b32_e32 v54, v10
	v_mov_b32_e32 v55, v10
	v_mov_b32_e32 v56, v10
	v_mov_b32_e32 v57, v10
	v_mov_b32_e32 v66, v10
	v_mov_b32_e32 v67, v10
	v_mov_b32_e32 v68, v10
	v_mov_b32_e32 v69, v10
	v_mov_b32_e32 v70, v10
	v_mov_b32_e32 v71, v10
	v_mov_b32_e32 v72, v10
	v_mov_b32_e32 v73, v10
	v_mov_b32_e32 v74, v10
	v_mov_b32_e32 v75, v10
	v_mov_b32_e32 v76, v10
	v_mov_b32_e32 v77, v10
	v_mov_b32_e32 v78, v10
	v_mov_b32_e32 v79, v10
	v_mov_b32_e32 v80, v10
	v_mov_b32_e32 v81, v10
	v_mov_b32_e32 v90, v10
	v_mov_b32_e32 v91, v10
	v_mov_b32_e32 v92, v10
	v_mov_b32_e32 v93, v10
	v_mov_b32_e32 v94, v10
	v_mov_b32_e32 v95, v10
	v_mov_b32_e32 v96, v10
	v_mov_b32_e32 v97, v10
	v_mov_b32_e32 v106, v10
	v_mov_b32_e32 v107, v10
	v_mov_b32_e32 v108, v10
	v_mov_b32_e32 v109, v10
	v_mov_b32_e32 v110, v10
	v_mov_b32_e32 v111, v10
	v_mov_b32_e32 v112, v10
	v_mov_b32_e32 v113, v10
	v_mov_b32_e32 v122, v10
	v_mov_b32_e32 v123, v10
	v_mov_b32_e32 v124, v10
	v_mov_b32_e32 v125, v10
	v_mov_b32_e32 v126, v10
	v_mov_b32_e32 v127, v10
	v_mov_b32_e32 v128, v10
	v_mov_b32_e32 v129, v10
	v_mov_b32_e32 v82, v10
	v_mov_b32_e32 v83, v10
	v_mov_b32_e32 v84, v10
	v_mov_b32_e32 v85, v10
	v_mov_b32_e32 v86, v10
	v_mov_b32_e32 v87, v10
	v_mov_b32_e32 v88, v10
	v_mov_b32_e32 v89, v10
	v_mov_b32_e32 v98, v10
	v_mov_b32_e32 v99, v10
	v_mov_b32_e32 v100, v10
	v_mov_b32_e32 v101, v10
	v_mov_b32_e32 v102, v10
	v_mov_b32_e32 v103, v10
	v_mov_b32_e32 v104, v10
	v_mov_b32_e32 v105, v10
	v_mov_b32_e32 v114, v10
	v_mov_b32_e32 v115, v10
	v_mov_b32_e32 v116, v10
	v_mov_b32_e32 v117, v10
	v_mov_b32_e32 v118, v10
	v_mov_b32_e32 v119, v10
	v_mov_b32_e32 v120, v10
	v_mov_b32_e32 v121, v10
	v_mov_b32_e32 v130, v10
	v_mov_b32_e32 v131, v10
	v_mov_b32_e32 v132, v10
	v_mov_b32_e32 v133, v10
	v_mov_b32_e32 v134, v10
	v_mov_b32_e32 v135, v10
	v_mov_b32_e32 v136, v10
	v_mov_b32_e32 v137, v10
	v_readfirstlane_b32 vcc_lo, v0
	s_lshr_b32 vcc_lo, vcc_lo, 6
	s_cmp_ge_u32 vcc_lo, 4
	s_cbranch_scc0 .Lsp_skip_297
	s_setprio 1
.Lsp_skip_297:
.LBB0_297:
	s_add_i32 vcc_lo, s82, 2
	s_add_u32 s80, s0, 0x80
	s_addc_u32 s81, s1, 0
	s_cmp_eq_u32 s72, s82
	s_cselect_b32 s83, s25, s81
	s_cselect_b32 s82, s24, s80
	v_add_u32_e32 v146, s91, v153
	s_cselect_b32 s81, s85, s87
	s_cselect_b32 s80, s84, s86
	s_add_i32 vcc_hi, 0, 0x14000
	ds_read_b128 v[156:159], v146
	ds_read_b128 v[160:163], v146 offset:1024
	ds_read_b128 v[164:167], v146 offset:2048
	ds_read_b128 v[176:179], v146 offset:3072
	v_add_u32_e32 v146, vcc_hi, v153
	ds_read_b128 v[180:183], v146
	ds_read_b128 v[184:187], v146 offset:1024
	ds_read_b128 v[188:191], v146 offset:2048
	ds_read_b128 v[192:195], v146 offset:3072
	v_lshl_add_u64 v[146:147], s[0:1], 0, v[142:143]
	s_add_i32 m0, s26, 0xc000
	ds_read_b128 v[196:199], v154
	ds_read_b128 v[200:203], v154 offset:1024
	ds_read_b128 v[220:223], v154 offset:2048
	ds_read_b128 v[224:227], v154 offset:3072
	ds_read_b128 v[228:231], v154 offset:4096
	ds_read_b128 v[232:235], v154 offset:5120
	ds_read_b128 v[236:239], v154 offset:6144
	ds_read_b128 v[244:247], v154 offset:7168
	global_load_lds_dwordx4 v[146:147], off
	v_lshl_add_u64 v[146:147], s[0:1], 0, v[144:145]
	s_add_i32 m0, s26, 0xe000
	s_nop 0
	global_load_lds_dwordx4 v[146:147], off
	s_waitcnt vmcnt(8)
	s_waitcnt lgkmcnt(0)
	s_barrier
; #define PG8_STAGE(bufoff, gbase, voff) do { _Pragma("unroll") for (int _i = 0; _i < 2; ++_i) \
;         __builtin_amdgcn_global_load_lds((const unsigned*)((const char*)(gbase) + (voff)[_i]), (LAS unsigned*)(lds + (bufoff) + ldsw + _i * 8192), 16, 0, 0); } while (0)
; #define PG8_LDA(dst, b, h) do { _Pragma("unroll") for (int m = 0; m < 4; ++m) _Pragma("unroll") for (int k = 0; k < 2; ++k) dst[m][k] = *(const LAS bf16x8*)(lds + PG8_SA(b, h) + aoff + m * 2048 + k * 1024); } while (0)
; #define PG8_MMA(ai, bj, At, Bt) do { __builtin_amdgcn_s_setprio(1); _Pragma("unroll") for (int m = 0; m < 4; ++m) _Pragma("unroll") for (int n = 0; n < 2; ++n) _Pragma("unroll") for (int k = 0; k < 2; ++k) \
;         acc[ai][bj][m][n] = __builtin_amdgcn_mfma_f32_16x16x32_bf16(Bt[n][k], At[m][k], acc[ai][bj][m][n], 0, 0, 0); __builtin_amdgcn_s_setprio(0); } while (0)
; #define PG8_WAIT_V(n) asm volatile("s_waitcnt vmcnt(" #n ")" ::: "memory")
; #define PG8_WAIT_L(n) asm volatile("s_waitcnt lgkmcnt(" #n ")" ::: "memory")
; #define PG8_BAR __builtin_amdgcn_s_barrier()
; #define PG8_SCHED __builtin_amdgcn_sched_barrier(0)
; template <class Epi, bool ALIGN_EPI = true>
; __device__ __forceinline__ void gemm_phase(LAS unsigned char* lds, const Gemm g, const StaticOrder& S, const Epi& E) {
;     ...
;             PG8_WAIT_V(8); PG8_WAIT_L(0); PG8_BAR; PG8_MMA(0, 0, At, B0); PG8_MMA(0, 1, At, B1); PG8_BAR; PG8_SCHED;
;             PG8_LDA(At, 0, 1); PG8_STAGE(PG8_SB(0, 0), b2, voffB); PG8_STAGE(PG8_SB(0, 1), b2 + hsB, voffB); PG8_STAGE(PG8_SA(0, 0), a2, voffA);
;             PG8_WAIT_V(8); PG8_WAIT_L(0); PG8_BAR; PG8_MMA(1, 0, At, B0); PG8_MMA(1, 1, At, B1); PG8_BAR; PG8_SCHED;
	s_waitcnt lgkmcnt(0)
	v_mfma_f32_16x16x32_bf16 v[134:137], v[156:159], v[196:199], v[134:137]
	v_mfma_f32_16x16x32_bf16 v[130:133], v[164:167], v[196:199], v[130:133]
	v_mfma_f32_16x16x32_bf16 v[118:121], v[156:159], v[220:223], v[118:121]
	v_mfma_f32_16x16x32_bf16 v[114:117], v[164:167], v[220:223], v[114:117]
	v_mfma_f32_16x16x32_bf16 v[102:105], v[156:159], v[228:231], v[102:105]
	v_mfma_f32_16x16x32_bf16 v[98:101], v[164:167], v[228:231], v[98:101]
	v_mfma_f32_16x16x32_bf16 v[86:89], v[156:159], v[236:239], v[86:89]
	v_mfma_f32_16x16x32_bf16 v[82:85], v[164:167], v[236:239], v[82:85]
	v_mfma_f32_16x16x32_bf16 v[134:137], v[160:163], v[200:203], v[134:137]
	v_mfma_f32_16x16x32_bf16 v[130:133], v[176:179], v[200:203], v[130:133]
	v_mfma_f32_16x16x32_bf16 v[118:121], v[160:163], v[224:227], v[118:121]
	v_mfma_f32_16x16x32_bf16 v[114:117], v[176:179], v[224:227], v[114:117]
	v_mfma_f32_16x16x32_bf16 v[102:105], v[160:163], v[232:235], v[102:105]
	v_mfma_f32_16x16x32_bf16 v[98:101], v[176:179], v[232:235], v[98:101]
	v_mfma_f32_16x16x32_bf16 v[86:89], v[160:163], v[244:247], v[86:89]
	v_mfma_f32_16x16x32_bf16 v[82:85], v[176:179], v[244:247], v[82:85]
	v_mfma_f32_16x16x32_bf16 v[126:129], v[180:183], v[196:199], v[126:129]
	v_mfma_f32_16x16x32_bf16 v[122:125], v[188:191], v[196:199], v[122:125]
	v_mfma_f32_16x16x32_bf16 v[110:113], v[180:183], v[220:223], v[110:113]
	v_mfma_f32_16x16x32_bf16 v[106:109], v[188:191], v[220:223], v[106:109]
	v_mfma_f32_16x16x32_bf16 v[94:97], v[180:183], v[228:231], v[94:97]
	v_mfma_f32_16x16x32_bf16 v[90:93], v[188:191], v[228:231], v[90:93]
	v_mfma_f32_16x16x32_bf16 v[78:81], v[180:183], v[236:239], v[78:81]
	v_mfma_f32_16x16x32_bf16 v[74:77], v[188:191], v[236:239], v[74:77]
	v_mfma_f32_16x16x32_bf16 v[126:129], v[184:187], v[200:203], v[126:129]
	v_mfma_f32_16x16x32_bf16 v[122:125], v[192:195], v[200:203], v[122:125]
	v_mfma_f32_16x16x32_bf16 v[110:113], v[184:187], v[224:227], v[110:113]
	v_mfma_f32_16x16x32_bf16 v[106:109], v[192:195], v[224:227], v[106:109]
	v_mfma_f32_16x16x32_bf16 v[94:97], v[184:187], v[232:235], v[94:97]
	v_mfma_f32_16x16x32_bf16 v[90:93], v[192:195], v[232:235], v[90:93]
	v_mfma_f32_16x16x32_bf16 v[78:81], v[184:187], v[244:247], v[78:81]
	v_mfma_f32_16x16x32_bf16 v[74:77], v[192:195], v[244:247], v[74:77]
	s_barrier
	s_add_i32 s97, s91, s10
	v_lshl_add_u64 v[146:147], s[80:81], 0, v[2:3]
	s_mov_b32 m0, s97
	ds_read_b128 v[196:199], v154 offset:16384
	ds_read_b128 v[200:203], v154 offset:17408
	ds_read_b128 v[220:223], v154 offset:18432
	ds_read_b128 v[224:227], v154 offset:19456
	ds_read_b128 v[228:231], v154 offset:20480
	ds_read_b128 v[232:235], v154 offset:21504
	ds_read_b128 v[236:239], v154 offset:22528
	ds_read_b128 v[244:247], v154 offset:23552
	global_load_lds_dwordx4 v[146:147], off
	s_add_i32 m0, s97, 0x2000
	v_lshl_add_u64 v[150:151], s[80:81], 0, v[4:5]
	s_add_u32 s80, s80, s96
	s_addc_u32 s81, s81, 0
	s_add_i32 s97, vcc_hi, s10
	global_load_lds_dwordx4 v[150:151], off
	v_lshl_add_u64 v[168:169], s[80:81], 0, v[2:3]
	s_mov_b32 m0, s97
	v_lshl_add_u64 v[172:173], s[80:81], 0, v[4:5]
	global_load_lds_dwordx4 v[168:169], off
	s_add_i32 m0, s97, 0x2000
	v_lshl_add_u64 v[240:241], s[82:83], 0, v[140:141]
	global_load_lds_dwordx4 v[172:173], off
	s_mov_b32 m0, s26
	v_lshl_add_u64 v[248:249], s[82:83], 0, v[138:139]
	global_load_lds_dwordx4 v[240:241], off
	s_mov_b32 m0, s68
	s_nop 0
	global_load_lds_dwordx4 v[248:249], off
	s_waitcnt vmcnt(8)
	s_waitcnt lgkmcnt(0)
	s_barrier
	s_waitcnt lgkmcnt(0)
	v_mfma_f32_16x16x32_bf16 v[70:73], v[156:159], v[196:199], v[70:73]
	v_mfma_f32_16x16x32_bf16 v[66:69], v[164:167], v[196:199], v[66:69]
	v_mfma_f32_16x16x32_bf16 v[54:57], v[156:159], v[220:223], v[54:57]
	v_mfma_f32_16x16x32_bf16 v[50:53], v[164:167], v[220:223], v[50:53]
	v_mfma_f32_16x16x32_bf16 v[38:41], v[156:159], v[228:231], v[38:41]
	v_mfma_f32_16x16x32_bf16 v[34:37], v[164:167], v[228:231], v[34:37]
	v_mfma_f32_16x16x32_bf16 v[22:25], v[156:159], v[236:239], v[22:25]
	v_mfma_f32_16x16x32_bf16 v[18:21], v[164:167], v[236:239], v[18:21]
	v_mfma_f32_16x16x32_bf16 v[70:73], v[160:163], v[200:203], v[70:73]
	v_mfma_f32_16x16x32_bf16 v[66:69], v[176:179], v[200:203], v[66:69]
	v_mfma_f32_16x16x32_bf16 v[54:57], v[160:163], v[224:227], v[54:57]
	v_mfma_f32_16x16x32_bf16 v[50:53], v[176:179], v[224:227], v[50:53]
	v_mfma_f32_16x16x32_bf16 v[38:41], v[160:163], v[232:235], v[38:41]
	v_mfma_f32_16x16x32_bf16 v[34:37], v[176:179], v[232:235], v[34:37]
	v_mfma_f32_16x16x32_bf16 v[22:25], v[160:163], v[244:247], v[22:25]
	v_mfma_f32_16x16x32_bf16 v[18:21], v[176:179], v[244:247], v[18:21]
	v_mfma_f32_16x16x32_bf16 v[62:65], v[180:183], v[196:199], v[62:65]
	v_mfma_f32_16x16x32_bf16 v[58:61], v[188:191], v[196:199], v[58:61]
	v_mfma_f32_16x16x32_bf16 v[46:49], v[180:183], v[220:223], v[46:49]
	v_mfma_f32_16x16x32_bf16 v[42:45], v[188:191], v[220:223], v[42:45]
	v_mfma_f32_16x16x32_bf16 v[30:33], v[180:183], v[228:231], v[30:33]
	v_mfma_f32_16x16x32_bf16 v[26:29], v[188:191], v[228:231], v[26:29]
	v_mfma_f32_16x16x32_bf16 v[14:17], v[180:183], v[236:239], v[14:17]
	v_mfma_f32_16x16x32_bf16 v[10:13], v[188:191], v[236:239], v[10:13]
	v_mfma_f32_16x16x32_bf16 v[62:65], v[184:187], v[200:203], v[62:65]
	v_mfma_f32_16x16x32_bf16 v[58:61], v[192:195], v[200:203], v[58:61]
	v_mfma_f32_16x16x32_bf16 v[46:49], v[184:187], v[224:227], v[46:49]
	v_mfma_f32_16x16x32_bf16 v[42:45], v[192:195], v[224:227], v[42:45]
	v_mfma_f32_16x16x32_bf16 v[30:33], v[184:187], v[232:235], v[30:33]
	v_mfma_f32_16x16x32_bf16 v[26:29], v[192:195], v[232:235], v[26:29]
	v_mfma_f32_16x16x32_bf16 v[14:17], v[184:187], v[244:247], v[14:17]
	v_mfma_f32_16x16x32_bf16 v[10:13], v[192:195], v[244:247], v[10:13]
	s_barrier
; #define PG8_STAGE(bufoff, gbase, voff) do { _Pragma("unroll") for (int _i = 0; _i < 2; ++_i) \
;         __builtin_amdgcn_global_load_lds((const unsigned*)((const char*)(gbase) + (voff)[_i]), (LAS unsigned*)(lds + (bufoff) + ldsw + _i * 8192), 16, 0, 0); } while (0)
; #define PG8_LDA(dst, b, h) do { _Pragma("unroll") for (int m = 0; m < 4; ++m) _Pragma("unroll") for (int k = 0; k < 2; ++k) dst[m][k] = *(const LAS bf16x8*)(lds + PG8_SA(b, h) + aoff + m * 2048 + k * 1024); } while (0)
; #define PG8_LDB(dst, b, h) do { _Pragma("unroll") for (int n = 0; n < 2; ++n) _Pragma("unroll") for (int k = 0; k < 2; ++k) dst[n][k] = *(const LAS bf16x8*)(lds + PG8_SB(b, h) + boff + n * 2048 + k * 1024); } while (0)
; #define PG8_MMA(ai, bj, At, Bt) do { __builtin_amdgcn_s_setprio(1); _Pragma("unroll") for (int m = 0; m < 4; ++m) _Pragma("unroll") for (int n = 0; n < 2; ++n) _Pragma("unroll") for (int k = 0; k < 2; ++k) \
;         acc[ai][bj][m][n] = __builtin_amdgcn_mfma_f32_16x16x32_bf16(Bt[n][k], At[m][k], acc[ai][bj][m][n], 0, 0, 0); __builtin_amdgcn_s_setprio(0); } while (0)
; #define PG8_WAIT_V(n) asm volatile("s_waitcnt vmcnt(" #n ")" ::: "memory")
; #define PG8_WAIT_L(n) asm volatile("s_waitcnt lgkmcnt(" #n ")" ::: "memory")
; #define PG8_BAR __builtin_amdgcn_s_barrier()
; #define PG8_SCHED __builtin_amdgcn_sched_barrier(0)
; template <class Epi, bool ALIGN_EPI = true>
; __device__ __forceinline__ void gemm_phase(LAS unsigned char* lds, const Gemm g, const StaticOrder& S, const Epi& E) {
;     ...
;             PG8_LDB(B0, 1, 0); PG8_LDB(B1, 1, 1); PG8_SCHED; PG8_LDA(At, 1, 0); PG8_STAGE(PG8_SA(0, 1), a2 + hsA, voffA);
;             PG8_WAIT_V(8); PG8_WAIT_L(0); PG8_BAR; PG8_MMA(0, 0, At, B0); PG8_MMA(0, 1, At, B1); PG8_BAR; PG8_SCHED;
	s_add_i32 s97, 0, 0x18000
	v_add_u32_e32 v148, s97, v153
	s_add_i32 vcc_hi, 0, 0x1c000
	ds_read_b128 v[156:159], v148
	ds_read_b128 v[160:163], v148 offset:1024
	ds_read_b128 v[164:167], v148 offset:2048
	ds_read_b128 v[176:179], v148 offset:3072
	v_add_u32_e32 v148, vcc_hi, v153
	ds_read_b128 v[180:183], v148
	ds_read_b128 v[184:187], v148 offset:1024
	ds_read_b128 v[188:191], v148 offset:2048
	ds_read_b128 v[192:195], v148 offset:3072
	s_add_u32 s80, s82, s14
	s_addc_u32 s81, s83, 0
	s_mov_b32 m0, s69
	v_lshl_add_u64 v[250:251], s[80:81], 0, v[140:141]
	ds_read_b128 v[196:199], v154 offset:32768
	ds_read_b128 v[200:203], v154 offset:33792
	ds_read_b128 v[220:223], v154 offset:34816
	ds_read_b128 v[224:227], v154 offset:35840
	ds_read_b128 v[228:231], v154 offset:36864
	ds_read_b128 v[232:235], v154 offset:37888
	ds_read_b128 v[236:239], v154 offset:38912
	ds_read_b128 v[244:247], v154 offset:39936
	global_load_lds_dwordx4 v[250:251], off
	v_lshl_add_u64 v[250:251], s[80:81], 0, v[138:139]
	s_mov_b32 m0, s73
	s_nop 0
	global_load_lds_dwordx4 v[250:251], off
	s_waitcnt vmcnt(8)
	s_waitcnt lgkmcnt(0)
	s_barrier
	s_waitcnt lgkmcnt(0)
	v_mfma_f32_16x16x32_bf16 v[134:137], v[156:159], v[196:199], v[134:137]
	v_mfma_f32_16x16x32_bf16 v[130:133], v[164:167], v[196:199], v[130:133]
	v_mfma_f32_16x16x32_bf16 v[118:121], v[156:159], v[220:223], v[118:121]
	v_mfma_f32_16x16x32_bf16 v[114:117], v[164:167], v[220:223], v[114:117]
	v_mfma_f32_16x16x32_bf16 v[102:105], v[156:159], v[228:231], v[102:105]
	v_mfma_f32_16x16x32_bf16 v[98:101], v[164:167], v[228:231], v[98:101]
	v_mfma_f32_16x16x32_bf16 v[86:89], v[156:159], v[236:239], v[86:89]
	v_mfma_f32_16x16x32_bf16 v[82:85], v[164:167], v[236:239], v[82:85]
	v_mfma_f32_16x16x32_bf16 v[134:137], v[160:163], v[200:203], v[134:137]
	v_mfma_f32_16x16x32_bf16 v[130:133], v[176:179], v[200:203], v[130:133]
	v_mfma_f32_16x16x32_bf16 v[118:121], v[160:163], v[224:227], v[118:121]
	v_mfma_f32_16x16x32_bf16 v[114:117], v[176:179], v[224:227], v[114:117]
	v_mfma_f32_16x16x32_bf16 v[102:105], v[160:163], v[232:235], v[102:105]
	v_mfma_f32_16x16x32_bf16 v[98:101], v[176:179], v[232:235], v[98:101]
	v_mfma_f32_16x16x32_bf16 v[86:89], v[160:163], v[244:247], v[86:89]
	v_mfma_f32_16x16x32_bf16 v[82:85], v[176:179], v[244:247], v[82:85]
	v_mfma_f32_16x16x32_bf16 v[126:129], v[180:183], v[196:199], v[126:129]
	v_mfma_f32_16x16x32_bf16 v[122:125], v[188:191], v[196:199], v[122:125]
	v_mfma_f32_16x16x32_bf16 v[110:113], v[180:183], v[220:223], v[110:113]
	v_mfma_f32_16x16x32_bf16 v[106:109], v[188:191], v[220:223], v[106:109]
	v_mfma_f32_16x16x32_bf16 v[94:97], v[180:183], v[228:231], v[94:97]
	v_mfma_f32_16x16x32_bf16 v[90:93], v[188:191], v[228:231], v[90:93]
	v_mfma_f32_16x16x32_bf16 v[78:81], v[180:183], v[236:239], v[78:81]
	v_mfma_f32_16x16x32_bf16 v[74:77], v[188:191], v[236:239], v[74:77]
	v_mfma_f32_16x16x32_bf16 v[126:129], v[184:187], v[200:203], v[126:129]
	v_mfma_f32_16x16x32_bf16 v[122:125], v[192:195], v[200:203], v[122:125]
	v_mfma_f32_16x16x32_bf16 v[110:113], v[184:187], v[224:227], v[110:113]
	v_mfma_f32_16x16x32_bf16 v[106:109], v[192:195], v[224:227], v[106:109]
	v_mfma_f32_16x16x32_bf16 v[94:97], v[184:187], v[232:235], v[94:97]
	v_mfma_f32_16x16x32_bf16 v[90:93], v[192:195], v[232:235], v[90:93]
	v_mfma_f32_16x16x32_bf16 v[78:81], v[184:187], v[244:247], v[78:81]
	v_mfma_f32_16x16x32_bf16 v[74:77], v[192:195], v[244:247], v[74:77]
	s_barrier
; #define PG8_STAGE(bufoff, gbase, voff) do { _Pragma("unroll") for (int _i = 0; _i < 2; ++_i) \
;         __builtin_amdgcn_global_load_lds((const unsigned*)((const char*)(gbase) + (voff)[_i]), (LAS unsigned*)(lds + (bufoff) + ldsw + _i * 8192), 16, 0, 0); } while (0)
; #define PG8_LDA(dst, b, h) do { _Pragma("unroll") for (int m = 0; m < 4; ++m) _Pragma("unroll") for (int k = 0; k < 2; ++k) dst[m][k] = *(const LAS bf16x8*)(lds + PG8_SA(b, h) + aoff + m * 2048 + k * 1024); } while (0)
; #define PG8_MMA(ai, bj, At, Bt) do { __builtin_amdgcn_s_setprio(1); _Pragma("unroll") for (int m = 0; m < 4; ++m) _Pragma("unroll") for (int n = 0; n < 2; ++n) _Pragma("unroll") for (int k = 0; k < 2; ++k) \
;         acc[ai][bj][m][n] = __builtin_amdgcn_mfma_f32_16x16x32_bf16(Bt[n][k], At[m][k], acc[ai][bj][m][n], 0, 0, 0); __builtin_amdgcn_s_setprio(0); } while (0)
; #define PG8_WAIT_V(n) asm volatile("s_waitcnt vmcnt(" #n ")" ::: "memory")
; #define PG8_WAIT_L(n) asm volatile("s_waitcnt lgkmcnt(" #n ")" ::: "memory")
; #define PG8_BAR __builtin_amdgcn_s_barrier()
; #define PG8_SCHED __builtin_amdgcn_sched_barrier(0)
; template <class Epi, bool ALIGN_EPI = true>
; __device__ __forceinline__ void gemm_phase(LAS unsigned char* lds, const Gemm g, const StaticOrder& S, const Epi& E) {
;     ...
;             PG8_LDA(At, 1, 1); PG8_STAGE(PG8_SB(1, 0), b3, voffB); PG8_STAGE(PG8_SB(1, 1), b3 + hsB, voffB); PG8_STAGE(PG8_SA(1, 0), a3, voffA);
;             PG8_WAIT_V(8); PG8_WAIT_L(0); PG8_BAR; PG8_MMA(1, 0, At, B0); PG8_MMA(1, 1, At, B1); PG8_BAR; PG8_SCHED;
;         }
;         if constexpr (ALIGN_EPI) { if (wr == 0) PG8_BAR; }
;         if constexpr (!Epi::AFTER_DRAIN) E.fast(acc, cur, wr, wc, fr, fq, rsc);
;         if (!has_next) break;
	s_add_i32 s80, s97, s10
	v_lshl_add_u64 v[146:147], v[146:147], 0, s[70:71]
	s_mov_b32 m0, s80
	ds_read_b128 v[196:199], v154 offset:49152
	ds_read_b128 v[200:203], v154 offset:50176
	ds_read_b128 v[220:223], v154 offset:51200
	ds_read_b128 v[224:227], v154 offset:52224
	ds_read_b128 v[228:231], v154 offset:53248
	ds_read_b128 v[232:235], v154 offset:54272
	ds_read_b128 v[236:239], v154 offset:55296
	ds_read_b128 v[244:247], v154 offset:56320
	global_load_lds_dwordx4 v[146:147], off
	v_lshl_add_u64 v[146:147], v[150:151], 0, s[70:71]
	s_add_i32 m0, s80, 0x2000
	s_add_i32 s80, vcc_hi, s10
	global_load_lds_dwordx4 v[146:147], off
	v_lshl_add_u64 v[146:147], v[168:169], 0, s[70:71]
	s_mov_b32 m0, s80
	s_nop 0
	global_load_lds_dwordx4 v[146:147], off
	v_lshl_add_u64 v[146:147], v[172:173], 0, s[70:71]
	s_add_i32 m0, s80, 0x2000
	s_nop 0
	global_load_lds_dwordx4 v[146:147], off
	v_lshl_add_u64 v[146:147], v[240:241], 0, s[70:71]
	s_mov_b32 m0, s93
	s_nop 0
	global_load_lds_dwordx4 v[146:147], off
	v_lshl_add_u64 v[146:147], v[248:249], 0, s[70:71]
	s_mov_b32 m0, s74
	s_nop 0
	global_load_lds_dwordx4 v[146:147], off
	s_waitcnt vmcnt(8)
	s_waitcnt lgkmcnt(0)
	s_barrier
	s_waitcnt lgkmcnt(0)
	v_mfma_f32_16x16x32_bf16 v[70:73], v[156:159], v[196:199], v[70:73]
	v_mfma_f32_16x16x32_bf16 v[66:69], v[164:167], v[196:199], v[66:69]
	v_mfma_f32_16x16x32_bf16 v[54:57], v[156:159], v[220:223], v[54:57]
	v_mfma_f32_16x16x32_bf16 v[50:53], v[164:167], v[220:223], v[50:53]
	v_mfma_f32_16x16x32_bf16 v[38:41], v[156:159], v[228:231], v[38:41]
	v_mfma_f32_16x16x32_bf16 v[34:37], v[164:167], v[228:231], v[34:37]
	v_mfma_f32_16x16x32_bf16 v[22:25], v[156:159], v[236:239], v[22:25]
	v_mfma_f32_16x16x32_bf16 v[18:21], v[164:167], v[236:239], v[18:21]
	v_mfma_f32_16x16x32_bf16 v[70:73], v[160:163], v[200:203], v[70:73]
	v_mfma_f32_16x16x32_bf16 v[66:69], v[176:179], v[200:203], v[66:69]
	v_mfma_f32_16x16x32_bf16 v[54:57], v[160:163], v[224:227], v[54:57]
	v_mfma_f32_16x16x32_bf16 v[50:53], v[176:179], v[224:227], v[50:53]
	v_mfma_f32_16x16x32_bf16 v[38:41], v[160:163], v[232:235], v[38:41]
	v_mfma_f32_16x16x32_bf16 v[34:37], v[176:179], v[232:235], v[34:37]
	v_mfma_f32_16x16x32_bf16 v[22:25], v[160:163], v[244:247], v[22:25]
	v_mfma_f32_16x16x32_bf16 v[18:21], v[176:179], v[244:247], v[18:21]
	v_mfma_f32_16x16x32_bf16 v[62:65], v[180:183], v[196:199], v[62:65]
	v_mfma_f32_16x16x32_bf16 v[58:61], v[188:191], v[196:199], v[58:61]
	v_mfma_f32_16x16x32_bf16 v[46:49], v[180:183], v[220:223], v[46:49]
	v_mfma_f32_16x16x32_bf16 v[42:45], v[188:191], v[220:223], v[42:45]
	v_mfma_f32_16x16x32_bf16 v[30:33], v[180:183], v[228:231], v[30:33]
	v_mfma_f32_16x16x32_bf16 v[26:29], v[188:191], v[228:231], v[26:29]
	v_mfma_f32_16x16x32_bf16 v[14:17], v[180:183], v[236:239], v[14:17]
	v_mfma_f32_16x16x32_bf16 v[10:13], v[188:191], v[236:239], v[10:13]
	v_mfma_f32_16x16x32_bf16 v[62:65], v[184:187], v[200:203], v[62:65]
	v_mfma_f32_16x16x32_bf16 v[58:61], v[192:195], v[200:203], v[58:61]
	v_mfma_f32_16x16x32_bf16 v[46:49], v[184:187], v[224:227], v[46:49]
	v_mfma_f32_16x16x32_bf16 v[42:45], v[192:195], v[224:227], v[42:45]
	v_mfma_f32_16x16x32_bf16 v[30:33], v[184:187], v[232:235], v[30:33]
	v_mfma_f32_16x16x32_bf16 v[26:29], v[192:195], v[232:235], v[26:29]
	v_mfma_f32_16x16x32_bf16 v[14:17], v[184:187], v[244:247], v[14:17]
	v_mfma_f32_16x16x32_bf16 v[10:13], v[192:195], v[244:247], v[10:13]
	s_barrier
	s_add_u32 s0, s0, 0x100
	s_addc_u32 s1, s1, 0
	s_add_u32 s86, s86, 0x100
	s_addc_u32 s87, s87, 0
	s_cmp_ge_u32 vcc_lo, s95
	s_mov_b32 s82, vcc_lo
	s_cbranch_scc0 .LBB0_297
	s_setprio 0
	s_and_b64 vcc, exec, s[22:23]
	s_cbranch_vccz .LBB0_300
	s_barrier

; #define PG8_STAGE(bufoff, gbase, voff) do { _Pragma("unroll") for (int _i = 0; _i < 2; ++_i) \
;         __builtin_amdgcn_global_load_lds((const unsigned*)((const char*)(gbase) + (voff)[_i]), (LAS unsigned*)(lds + (bufoff) + ldsw + _i * 8192), 16, 0, 0); } while (0)
; #define PG8_LDA(dst, b, h) do { _Pragma("unroll") for (int m = 0; m < 4; ++m) _Pragma("unroll") for (int k = 0; k < 2; ++k) dst[m][k] = *(const LAS bf16x8*)(lds + PG8_SA(b, h) + aoff + m * 2048 + k * 1024); } while (0)
; #define PG8_LDB(dst, b, h) do { _Pragma("unroll") for (int n = 0; n < 2; ++n) _Pragma("unroll") for (int k = 0; k < 2; ++k) dst[n][k] = *(const LAS bf16x8*)(lds + PG8_SB(b, h) + boff + n * 2048 + k * 1024); } while (0)
; #define PG8_SCHED __builtin_amdgcn_sched_barrier(0)
; template <class Epi, bool ALIGN_EPI = true>
; __device__ __forceinline__ void gemm_phase(LAS unsigned char* lds, const Gemm g, const StaticOrder& S, const Epi& E) {
;     ...
;         const bool has_next = S.next(ui + 1, nxt);
;         const char* nA = has_next ? (const char*)g.A + (size_t)nxt.pm * tsA : cA; const char* nB = has_next ? (const char*)g.Bt + (size_t)nxt.pn * tsB : cB;
;         for (int t = 0; t < nt; t += 2) {
;             const bool last = (t == nt - 2);
;             const char* a1 = cA + (size_t)(t + 1) * kstep;
;             const char* a2 = last ? nA : cA + (size_t)(t + 2) * kstep; const char* b2 = last ? nB : cB + (size_t)(t + 2) * kstep;
;             const char* a3 = a2 + kstep; const char* b3 = b2 + kstep;
;             PG8_LDB(B0, 0, 0); PG8_LDB(B1, 0, 1); PG8_SCHED; PG8_LDA(At, 0, 0); PG8_STAGE(PG8_SA(1, 1), a1 + hsA, voffA);
;     ...
; #pragma unroll
;         for (int a = 0; a < 2; ++a)
; #pragma unroll
;             for (int b = 0; b < 2; ++b)
; #pragma unroll
;                 for (int m = 0; m < 4; ++m)
; #pragma unroll
;                     for (int n = 0; n < 2; ++n) acc[a][b][m][n] = (f32x4){0.f, 0.f, 0.f, 0.f};
.LBB0_327:
	s_add_u32 s0, s84, 0x80
	s_addc_u32 s1, s85, 0
	s_add_u32 s3, s82, 0x100
	v_mov_b32_e32 v10, 0
	s_addc_u32 s10, s83, 0
	s_mov_b32 s11, 0
	v_mov_b32_e32 v11, v10
	v_mov_b32_e32 v12, v10
	v_mov_b32_e32 v13, v10
	v_mov_b32_e32 v14, v10
	v_mov_b32_e32 v15, v10
	v_mov_b32_e32 v16, v10
	v_mov_b32_e32 v17, v10
	v_mov_b32_e32 v26, v10
	v_mov_b32_e32 v27, v10
	v_mov_b32_e32 v28, v10
	v_mov_b32_e32 v29, v10
	v_mov_b32_e32 v30, v10
	v_mov_b32_e32 v31, v10
	v_mov_b32_e32 v32, v10
	v_mov_b32_e32 v33, v10
	v_mov_b32_e32 v38, v10
	v_mov_b32_e32 v39, v10
	v_mov_b32_e32 v40, v10
	v_mov_b32_e32 v41, v10
	v_mov_b32_e32 v46, v10
	v_mov_b32_e32 v47, v10
	v_mov_b32_e32 v48, v10
	v_mov_b32_e32 v49, v10
	v_mov_b32_e32 v54, v10
	v_mov_b32_e32 v55, v10
	v_mov_b32_e32 v56, v10
	v_mov_b32_e32 v57, v10
	v_mov_b32_e32 v62, v10
	v_mov_b32_e32 v63, v10
	v_mov_b32_e32 v64, v10
	v_mov_b32_e32 v65, v10
	v_mov_b32_e32 v18, v10
	v_mov_b32_e32 v19, v10
	v_mov_b32_e32 v20, v10
	v_mov_b32_e32 v21, v10
	v_mov_b32_e32 v22, v10
	v_mov_b32_e32 v23, v10
	v_mov_b32_e32 v24, v10
	v_mov_b32_e32 v25, v10
	v_mov_b32_e32 v34, v10
	v_mov_b32_e32 v35, v10
	v_mov_b32_e32 v36, v10
	v_mov_b32_e32 v37, v10
	v_mov_b32_e32 v42, v10
	v_mov_b32_e32 v43, v10
	v_mov_b32_e32 v44, v10
	v_mov_b32_e32 v45, v10
	v_mov_b32_e32 v50, v10
	v_mov_b32_e32 v51, v10
	v_mov_b32_e32 v52, v10
	v_mov_b32_e32 v53, v10
	v_mov_b32_e32 v58, v10
	v_mov_b32_e32 v59, v10
	v_mov_b32_e32 v60, v10
	v_mov_b32_e32 v61, v10
	v_mov_b32_e32 v66, v10
	v_mov_b32_e32 v67, v10
	v_mov_b32_e32 v68, v10
	v_mov_b32_e32 v69, v10
	v_mov_b32_e32 v70, v10
	v_mov_b32_e32 v71, v10
	v_mov_b32_e32 v72, v10
	v_mov_b32_e32 v73, v10
	v_mov_b32_e32 v74, v10
	v_mov_b32_e32 v75, v10
	v_mov_b32_e32 v76, v10
	v_mov_b32_e32 v77, v10
	v_mov_b32_e32 v78, v10
	v_mov_b32_e32 v79, v10
	v_mov_b32_e32 v80, v10
	v_mov_b32_e32 v81, v10
	v_mov_b32_e32 v90, v10
	v_mov_b32_e32 v91, v10
	v_mov_b32_e32 v92, v10
	v_mov_b32_e32 v93, v10
	v_mov_b32_e32 v94, v10
	v_mov_b32_e32 v95, v10
	v_mov_b32_e32 v96, v10
	v_mov_b32_e32 v97, v10
	v_mov_b32_e32 v102, v10
	v_mov_b32_e32 v103, v10
	v_mov_b32_e32 v104, v10
	v_mov_b32_e32 v105, v10
	v_mov_b32_e32 v110, v10
	v_mov_b32_e32 v111, v10
	v_mov_b32_e32 v112, v10
	v_mov_b32_e32 v113, v10
	v_mov_b32_e32 v118, v10
	v_mov_b32_e32 v119, v10
	v_mov_b32_e32 v120, v10
	v_mov_b32_e32 v121, v10
	v_mov_b32_e32 v126, v10
	v_mov_b32_e32 v127, v10
	v_mov_b32_e32 v128, v10
	v_mov_b32_e32 v129, v10
	v_mov_b32_e32 v82, v10
	v_mov_b32_e32 v83, v10
	v_mov_b32_e32 v84, v10
	v_mov_b32_e32 v85, v10
	v_mov_b32_e32 v86, v10
	v_mov_b32_e32 v87, v10
	v_mov_b32_e32 v88, v10
	v_mov_b32_e32 v89, v10
	v_mov_b32_e32 v98, v10
	v_mov_b32_e32 v99, v10
	v_mov_b32_e32 v100, v10
	v_mov_b32_e32 v101, v10
	v_mov_b32_e32 v106, v10
	v_mov_b32_e32 v107, v10
	v_mov_b32_e32 v108, v10
	v_mov_b32_e32 v109, v10
	v_mov_b32_e32 v114, v10
	v_mov_b32_e32 v115, v10
	v_mov_b32_e32 v116, v10
	v_mov_b32_e32 v117, v10
	v_mov_b32_e32 v122, v10
	v_mov_b32_e32 v123, v10
	v_mov_b32_e32 v124, v10
	v_mov_b32_e32 v125, v10
	v_mov_b32_e32 v130, v10
	v_mov_b32_e32 v131, v10
	v_mov_b32_e32 v132, v10
	v_mov_b32_e32 v133, v10
	v_mov_b32_e32 v134, v10
	v_mov_b32_e32 v135, v10
	v_mov_b32_e32 v136, v10
	v_mov_b32_e32 v137, v10
	v_readfirstlane_b32 s26, v0
	s_lshr_b32 s26, s26, 6
	s_cmp_ge_u32 s26, 4
	s_cbranch_scc0 .Lsp_skip_328
	s_setprio 1
.Lsp_skip_328:
.LBB0_328:
	s_add_i32 s26, s11, 2
	s_add_u32 s69, s0, 0x80
	s_addc_u32 s74, s1, 0
	s_cmp_eq_u32 s72, s11
	s_cselect_b32 s83, s23, s74
	s_cselect_b32 s82, s22, s69
	v_add_u32_e32 v2, s91, v176
	s_cselect_b32 s75, s25, s10
	s_cselect_b32 s74, s24, s3
	s_add_i32 s11, 0, 0x14000
	ds_read_b128 v[138:141], v2
	ds_read_b128 v[142:145], v2 offset:1024
	ds_read_b128 v[146:149], v2 offset:2048
	ds_read_b128 v[150:153], v2 offset:3072
	v_add_u32_e32 v2, s11, v176
	ds_read_b128 v[164:167], v2
	ds_read_b128 v[178:181], v2 offset:1024
	ds_read_b128 v[182:185], v2 offset:2048
	ds_read_b128 v[186:189], v2 offset:3072
	v_lshl_add_u64 v[202:203], s[0:1], 0, v[160:161]
	s_add_i32 m0, s86, 0xc000
	ds_read_b128 v[190:193], v1
	ds_read_b128 v[194:197], v1 offset:1024
	ds_read_b128 v[198:201], v1 offset:2048
	ds_read_b128 v[220:223], v1 offset:3072
	ds_read_b128 v[224:227], v1 offset:4096
	ds_read_b128 v[228:231], v1 offset:5120
	ds_read_b128 v[232:235], v1 offset:6144
	ds_read_b128 v[236:239], v1 offset:7168
	global_load_lds_dwordx4 v[202:203], off
	v_lshl_add_u64 v[202:203], s[0:1], 0, v[162:163]
	s_add_i32 m0, s86, 0xe000
	s_nop 0
	global_load_lds_dwordx4 v[202:203], off
	s_waitcnt vmcnt(8)
	s_waitcnt lgkmcnt(0)
	s_barrier
; #define PG8_STAGE(bufoff, gbase, voff) do { _Pragma("unroll") for (int _i = 0; _i < 2; ++_i) \
;         __builtin_amdgcn_global_load_lds((const unsigned*)((const char*)(gbase) + (voff)[_i]), (LAS unsigned*)(lds + (bufoff) + ldsw + _i * 8192), 16, 0, 0); } while (0)
; #define PG8_LDA(dst, b, h) do { _Pragma("unroll") for (int m = 0; m < 4; ++m) _Pragma("unroll") for (int k = 0; k < 2; ++k) dst[m][k] = *(const LAS bf16x8*)(lds + PG8_SA(b, h) + aoff + m * 2048 + k * 1024); } while (0)
; #define PG8_MMA(ai, bj, At, Bt) do { __builtin_amdgcn_s_setprio(1); _Pragma("unroll") for (int m = 0; m < 4; ++m) _Pragma("unroll") for (int n = 0; n < 2; ++n) _Pragma("unroll") for (int k = 0; k < 2; ++k) \
;         acc[ai][bj][m][n] = __builtin_amdgcn_mfma_f32_16x16x32_bf16(Bt[n][k], At[m][k], acc[ai][bj][m][n], 0, 0, 0); __builtin_amdgcn_s_setprio(0); } while (0)
; #define PG8_WAIT_V(n) asm volatile("s_waitcnt vmcnt(" #n ")" ::: "memory")
; #define PG8_WAIT_L(n) asm volatile("s_waitcnt lgkmcnt(" #n ")" ::: "memory")
; #define PG8_BAR __builtin_amdgcn_s_barrier()
; #define PG8_SCHED __builtin_amdgcn_sched_barrier(0)
; template <class Epi, bool ALIGN_EPI = true>
; __device__ __forceinline__ void gemm_phase(LAS unsigned char* lds, const Gemm g, const StaticOrder& S, const Epi& E) {
;     ...
;             PG8_WAIT_V(8); PG8_WAIT_L(0); PG8_BAR; PG8_MMA(0, 0, At, B0); PG8_MMA(0, 1, At, B1); PG8_BAR; PG8_SCHED;
;             PG8_LDA(At, 0, 1); PG8_STAGE(PG8_SB(0, 0), b2, voffB); PG8_STAGE(PG8_SB(0, 1), b2 + hsB, voffB); PG8_STAGE(PG8_SA(0, 0), a2, voffA);
;             PG8_WAIT_V(8); PG8_WAIT_L(0); PG8_BAR; PG8_MMA(1, 0, At, B0); PG8_MMA(1, 1, At, B1); PG8_BAR; PG8_SCHED;
	s_waitcnt lgkmcnt(0)
	v_mfma_f32_16x16x32_bf16 v[134:137], v[138:141], v[190:193], v[134:137]
	v_mfma_f32_16x16x32_bf16 v[130:133], v[146:149], v[190:193], v[130:133]
	v_mfma_f32_16x16x32_bf16 v[122:125], v[138:141], v[198:201], v[122:125]
	v_mfma_f32_16x16x32_bf16 v[114:117], v[146:149], v[198:201], v[114:117]
	v_mfma_f32_16x16x32_bf16 v[106:109], v[138:141], v[224:227], v[106:109]
	v_mfma_f32_16x16x32_bf16 v[98:101], v[146:149], v[224:227], v[98:101]
	v_mfma_f32_16x16x32_bf16 v[86:89], v[138:141], v[232:235], v[86:89]
	v_mfma_f32_16x16x32_bf16 v[82:85], v[146:149], v[232:235], v[82:85]
	v_mfma_f32_16x16x32_bf16 v[134:137], v[142:145], v[194:197], v[134:137]
	v_mfma_f32_16x16x32_bf16 v[130:133], v[150:153], v[194:197], v[130:133]
	v_mfma_f32_16x16x32_bf16 v[122:125], v[142:145], v[220:223], v[122:125]
	v_mfma_f32_16x16x32_bf16 v[114:117], v[150:153], v[220:223], v[114:117]
	v_mfma_f32_16x16x32_bf16 v[106:109], v[142:145], v[228:231], v[106:109]
	v_mfma_f32_16x16x32_bf16 v[98:101], v[150:153], v[228:231], v[98:101]
	v_mfma_f32_16x16x32_bf16 v[86:89], v[142:145], v[236:239], v[86:89]
	v_mfma_f32_16x16x32_bf16 v[82:85], v[150:153], v[236:239], v[82:85]
	v_mfma_f32_16x16x32_bf16 v[126:129], v[164:167], v[190:193], v[126:129]
	v_mfma_f32_16x16x32_bf16 v[118:121], v[182:185], v[190:193], v[118:121]
	v_mfma_f32_16x16x32_bf16 v[110:113], v[164:167], v[198:201], v[110:113]
	v_mfma_f32_16x16x32_bf16 v[102:105], v[182:185], v[198:201], v[102:105]
	v_mfma_f32_16x16x32_bf16 v[94:97], v[164:167], v[224:227], v[94:97]
	v_mfma_f32_16x16x32_bf16 v[90:93], v[182:185], v[224:227], v[90:93]
	v_mfma_f32_16x16x32_bf16 v[78:81], v[164:167], v[232:235], v[78:81]
	v_mfma_f32_16x16x32_bf16 v[74:77], v[182:185], v[232:235], v[74:77]
	v_mfma_f32_16x16x32_bf16 v[126:129], v[178:181], v[194:197], v[126:129]
	v_mfma_f32_16x16x32_bf16 v[118:121], v[186:189], v[194:197], v[118:121]
	v_mfma_f32_16x16x32_bf16 v[110:113], v[178:181], v[220:223], v[110:113]
	v_mfma_f32_16x16x32_bf16 v[102:105], v[186:189], v[220:223], v[102:105]
	v_mfma_f32_16x16x32_bf16 v[94:97], v[178:181], v[228:231], v[94:97]
	v_mfma_f32_16x16x32_bf16 v[90:93], v[186:189], v[228:231], v[90:93]
	v_mfma_f32_16x16x32_bf16 v[78:81], v[178:181], v[236:239], v[78:81]
	v_mfma_f32_16x16x32_bf16 v[74:77], v[186:189], v[236:239], v[74:77]
	s_barrier
	s_add_i32 s69, s91, s73
	v_lshl_add_u64 v[202:203], s[74:75], 0, v[154:155]
	s_mov_b32 m0, s69
	ds_read_b128 v[190:193], v1 offset:16384
	ds_read_b128 v[194:197], v1 offset:17408
	ds_read_b128 v[198:201], v1 offset:18432
	ds_read_b128 v[220:223], v1 offset:19456
	ds_read_b128 v[224:227], v1 offset:20480
	ds_read_b128 v[228:231], v1 offset:21504
	ds_read_b128 v[232:235], v1 offset:22528
	ds_read_b128 v[236:239], v1 offset:23552
	global_load_lds_dwordx4 v[202:203], off
	s_add_i32 m0, s69, 0x2000
	v_lshl_add_u64 v[240:241], s[74:75], 0, v[158:159]
	s_add_u32 s74, s74, s96
	s_addc_u32 s75, s75, 0
	s_add_i32 s11, s11, s73
	global_load_lds_dwordx4 v[240:241], off
	v_lshl_add_u64 v[244:245], s[74:75], 0, v[154:155]
	s_mov_b32 m0, s11
	v_lshl_add_u64 v[246:247], s[74:75], 0, v[158:159]
	global_load_lds_dwordx4 v[244:245], off
	s_add_i32 m0, s11, 0x2000
	v_lshl_add_u64 v[248:249], s[82:83], 0, v[4:5]
	global_load_lds_dwordx4 v[246:247], off
	s_mov_b32 m0, s86
	v_lshl_add_u64 v[250:251], s[82:83], 0, v[156:157]
	global_load_lds_dwordx4 v[248:249], off
	s_mov_b32 m0, s87
	s_nop 0
	global_load_lds_dwordx4 v[250:251], off
	s_waitcnt vmcnt(8)
	s_waitcnt lgkmcnt(0)
	s_barrier
	s_waitcnt lgkmcnt(0)
	v_mfma_f32_16x16x32_bf16 v[70:73], v[138:141], v[190:193], v[70:73]
	v_mfma_f32_16x16x32_bf16 v[66:69], v[146:149], v[190:193], v[66:69]
	v_mfma_f32_16x16x32_bf16 v[58:61], v[138:141], v[198:201], v[58:61]
	v_mfma_f32_16x16x32_bf16 v[50:53], v[146:149], v[198:201], v[50:53]
	v_mfma_f32_16x16x32_bf16 v[42:45], v[138:141], v[224:227], v[42:45]
	v_mfma_f32_16x16x32_bf16 v[34:37], v[146:149], v[224:227], v[34:37]
	v_mfma_f32_16x16x32_bf16 v[22:25], v[138:141], v[232:235], v[22:25]
	v_mfma_f32_16x16x32_bf16 v[18:21], v[146:149], v[232:235], v[18:21]
	v_mfma_f32_16x16x32_bf16 v[70:73], v[142:145], v[194:197], v[70:73]
	v_mfma_f32_16x16x32_bf16 v[66:69], v[150:153], v[194:197], v[66:69]
	v_mfma_f32_16x16x32_bf16 v[58:61], v[142:145], v[220:223], v[58:61]
	v_mfma_f32_16x16x32_bf16 v[50:53], v[150:153], v[220:223], v[50:53]
	v_mfma_f32_16x16x32_bf16 v[42:45], v[142:145], v[228:231], v[42:45]
	v_mfma_f32_16x16x32_bf16 v[34:37], v[150:153], v[228:231], v[34:37]
	v_mfma_f32_16x16x32_bf16 v[22:25], v[142:145], v[236:239], v[22:25]
	v_mfma_f32_16x16x32_bf16 v[18:21], v[150:153], v[236:239], v[18:21]
	v_mfma_f32_16x16x32_bf16 v[62:65], v[164:167], v[190:193], v[62:65]
	v_mfma_f32_16x16x32_bf16 v[54:57], v[182:185], v[190:193], v[54:57]
	v_mfma_f32_16x16x32_bf16 v[46:49], v[164:167], v[198:201], v[46:49]
	v_mfma_f32_16x16x32_bf16 v[38:41], v[182:185], v[198:201], v[38:41]
	v_mfma_f32_16x16x32_bf16 v[30:33], v[164:167], v[224:227], v[30:33]
	v_mfma_f32_16x16x32_bf16 v[26:29], v[182:185], v[224:227], v[26:29]
	v_mfma_f32_16x16x32_bf16 v[14:17], v[164:167], v[232:235], v[14:17]
	v_mfma_f32_16x16x32_bf16 v[10:13], v[182:185], v[232:235], v[10:13]
	v_mfma_f32_16x16x32_bf16 v[62:65], v[178:181], v[194:197], v[62:65]
	v_mfma_f32_16x16x32_bf16 v[54:57], v[186:189], v[194:197], v[54:57]
	v_mfma_f32_16x16x32_bf16 v[46:49], v[178:181], v[220:223], v[46:49]
	v_mfma_f32_16x16x32_bf16 v[38:41], v[186:189], v[220:223], v[38:41]
	v_mfma_f32_16x16x32_bf16 v[30:33], v[178:181], v[228:231], v[30:33]
	v_mfma_f32_16x16x32_bf16 v[26:29], v[186:189], v[228:231], v[26:29]
	v_mfma_f32_16x16x32_bf16 v[14:17], v[178:181], v[236:239], v[14:17]
	v_mfma_f32_16x16x32_bf16 v[10:13], v[186:189], v[236:239], v[10:13]
	s_barrier
; #define PG8_STAGE(bufoff, gbase, voff) do { _Pragma("unroll") for (int _i = 0; _i < 2; ++_i) \
;         __builtin_amdgcn_global_load_lds((const unsigned*)((const char*)(gbase) + (voff)[_i]), (LAS unsigned*)(lds + (bufoff) + ldsw + _i * 8192), 16, 0, 0); } while (0)
; #define PG8_LDA(dst, b, h) do { _Pragma("unroll") for (int m = 0; m < 4; ++m) _Pragma("unroll") for (int k = 0; k < 2; ++k) dst[m][k] = *(const LAS bf16x8*)(lds + PG8_SA(b, h) + aoff + m * 2048 + k * 1024); } while (0)
; #define PG8_LDB(dst, b, h) do { _Pragma("unroll") for (int n = 0; n < 2; ++n) _Pragma("unroll") for (int k = 0; k < 2; ++k) dst[n][k] = *(const LAS bf16x8*)(lds + PG8_SB(b, h) + boff + n * 2048 + k * 1024); } while (0)
; #define PG8_MMA(ai, bj, At, Bt) do { __builtin_amdgcn_s_setprio(1); _Pragma("unroll") for (int m = 0; m < 4; ++m) _Pragma("unroll") for (int n = 0; n < 2; ++n) _Pragma("unroll") for (int k = 0; k < 2; ++k) \
;         acc[ai][bj][m][n] = __builtin_amdgcn_mfma_f32_16x16x32_bf16(Bt[n][k], At[m][k], acc[ai][bj][m][n], 0, 0, 0); __builtin_amdgcn_s_setprio(0); } while (0)
; #define PG8_WAIT_V(n) asm volatile("s_waitcnt vmcnt(" #n ")" ::: "memory")
; #define PG8_WAIT_L(n) asm volatile("s_waitcnt lgkmcnt(" #n ")" ::: "memory")
; #define PG8_BAR __builtin_amdgcn_s_barrier()
; #define PG8_SCHED __builtin_amdgcn_sched_barrier(0)
; template <class Epi, bool ALIGN_EPI = true>
; __device__ __forceinline__ void gemm_phase(LAS unsigned char* lds, const Gemm g, const StaticOrder& S, const Epi& E) {
;     ...
;             PG8_LDB(B0, 1, 0); PG8_LDB(B1, 1, 1); PG8_SCHED; PG8_LDA(At, 1, 0); PG8_STAGE(PG8_SA(0, 1), a2 + hsA, voffA);
;             PG8_WAIT_V(8); PG8_WAIT_L(0); PG8_BAR; PG8_MMA(0, 0, At, B0); PG8_MMA(0, 1, At, B1); PG8_BAR; PG8_SCHED;
;             PG8_LDA(At, 1, 1); PG8_STAGE(PG8_SB(1, 0), b3, voffB); PG8_STAGE(PG8_SB(1, 1), b3 + hsB, voffB); PG8_STAGE(PG8_SA(1, 0), a3, voffA);
;             PG8_WAIT_V(8); PG8_WAIT_L(0); PG8_BAR; PG8_MMA(1, 0, At, B0); PG8_MMA(1, 1, At, B1); PG8_BAR; PG8_SCHED;
;         }
;         if constexpr (ALIGN_EPI) { if (wr == 0) PG8_BAR; }
;         if constexpr (!Epi::AFTER_DRAIN) E.fast(acc, cur, wr, wc, fr, fq, rsc);
;         if (!has_next) break;
	s_add_i32 s11, 0, 0x18000
	v_add_u32_e32 v2, s11, v176
	s_add_i32 s69, 0, 0x1c000
	ds_read_b128 v[138:141], v2
	ds_read_b128 v[142:145], v2 offset:1024
	ds_read_b128 v[146:149], v2 offset:2048
	ds_read_b128 v[150:153], v2 offset:3072
	v_add_u32_e32 v2, s69, v176
	ds_read_b128 v[164:167], v2
	ds_read_b128 v[178:181], v2 offset:1024
	ds_read_b128 v[182:185], v2 offset:2048
	ds_read_b128 v[186:189], v2 offset:3072
	s_add_u32 s74, s82, s14
	s_addc_u32 s75, s83, 0
	s_mov_b32 m0, s88
	v_lshl_add_u64 v[172:173], s[74:75], 0, v[4:5]
	ds_read_b128 v[190:193], v1 offset:32768
	ds_read_b128 v[194:197], v1 offset:33792
	ds_read_b128 v[198:201], v1 offset:34816
	ds_read_b128 v[220:223], v1 offset:35840
	ds_read_b128 v[224:227], v1 offset:36864
	ds_read_b128 v[228:231], v1 offset:37888
	ds_read_b128 v[232:235], v1 offset:38912
	ds_read_b128 v[236:239], v1 offset:39936
	global_load_lds_dwordx4 v[172:173], off
	v_lshl_add_u64 v[172:173], s[74:75], 0, v[156:157]
	s_mov_b32 m0, s89
	s_nop 0
	global_load_lds_dwordx4 v[172:173], off
	s_waitcnt vmcnt(8)
	s_waitcnt lgkmcnt(0)
	s_barrier
	s_waitcnt lgkmcnt(0)
	v_mfma_f32_16x16x32_bf16 v[134:137], v[138:141], v[190:193], v[134:137]
	v_mfma_f32_16x16x32_bf16 v[130:133], v[146:149], v[190:193], v[130:133]
	v_mfma_f32_16x16x32_bf16 v[122:125], v[138:141], v[198:201], v[122:125]
	v_mfma_f32_16x16x32_bf16 v[114:117], v[146:149], v[198:201], v[114:117]
	v_mfma_f32_16x16x32_bf16 v[106:109], v[138:141], v[224:227], v[106:109]
	v_mfma_f32_16x16x32_bf16 v[98:101], v[146:149], v[224:227], v[98:101]
	v_mfma_f32_16x16x32_bf16 v[86:89], v[138:141], v[232:235], v[86:89]
	v_mfma_f32_16x16x32_bf16 v[82:85], v[146:149], v[232:235], v[82:85]
	v_mfma_f32_16x16x32_bf16 v[134:137], v[142:145], v[194:197], v[134:137]
	v_mfma_f32_16x16x32_bf16 v[130:133], v[150:153], v[194:197], v[130:133]
	v_mfma_f32_16x16x32_bf16 v[122:125], v[142:145], v[220:223], v[122:125]
	v_mfma_f32_16x16x32_bf16 v[114:117], v[150:153], v[220:223], v[114:117]
	v_mfma_f32_16x16x32_bf16 v[106:109], v[142:145], v[228:231], v[106:109]
	v_mfma_f32_16x16x32_bf16 v[98:101], v[150:153], v[228:231], v[98:101]
	v_mfma_f32_16x16x32_bf16 v[86:89], v[142:145], v[236:239], v[86:89]
	v_mfma_f32_16x16x32_bf16 v[82:85], v[150:153], v[236:239], v[82:85]
	v_mfma_f32_16x16x32_bf16 v[126:129], v[164:167], v[190:193], v[126:129]
	v_mfma_f32_16x16x32_bf16 v[118:121], v[182:185], v[190:193], v[118:121]
	v_mfma_f32_16x16x32_bf16 v[110:113], v[164:167], v[198:201], v[110:113]
	v_mfma_f32_16x16x32_bf16 v[102:105], v[182:185], v[198:201], v[102:105]
	v_mfma_f32_16x16x32_bf16 v[94:97], v[164:167], v[224:227], v[94:97]
	v_mfma_f32_16x16x32_bf16 v[90:93], v[182:185], v[224:227], v[90:93]
	v_mfma_f32_16x16x32_bf16 v[78:81], v[164:167], v[232:235], v[78:81]
	v_mfma_f32_16x16x32_bf16 v[74:77], v[182:185], v[232:235], v[74:77]
	v_mfma_f32_16x16x32_bf16 v[126:129], v[178:181], v[194:197], v[126:129]
	v_mfma_f32_16x16x32_bf16 v[118:121], v[186:189], v[194:197], v[118:121]
	v_mfma_f32_16x16x32_bf16 v[110:113], v[178:181], v[220:223], v[110:113]
	v_mfma_f32_16x16x32_bf16 v[102:105], v[186:189], v[220:223], v[102:105]
	v_mfma_f32_16x16x32_bf16 v[94:97], v[178:181], v[228:231], v[94:97]
	v_mfma_f32_16x16x32_bf16 v[90:93], v[186:189], v[228:231], v[90:93]
	v_mfma_f32_16x16x32_bf16 v[78:81], v[178:181], v[236:239], v[78:81]
	v_mfma_f32_16x16x32_bf16 v[74:77], v[186:189], v[236:239], v[74:77]
	s_barrier
	s_add_i32 s11, s11, s73
	v_lshl_add_u64 v[172:173], v[202:203], 0, s[70:71]
	s_mov_b32 m0, s11
	ds_read_b128 v[190:193], v1 offset:49152
	ds_read_b128 v[194:197], v1 offset:50176
	ds_read_b128 v[198:201], v1 offset:51200
	ds_read_b128 v[220:223], v1 offset:52224
	ds_read_b128 v[224:227], v1 offset:53248
	ds_read_b128 v[228:231], v1 offset:54272
	ds_read_b128 v[232:235], v1 offset:55296
	ds_read_b128 v[236:239], v1 offset:56320
	global_load_lds_dwordx4 v[172:173], off
	v_lshl_add_u64 v[172:173], v[240:241], 0, s[70:71]
	s_add_i32 m0, s11, 0x2000
	s_add_i32 s11, s69, s73
	global_load_lds_dwordx4 v[172:173], off
	v_lshl_add_u64 v[172:173], v[244:245], 0, s[70:71]
	s_mov_b32 m0, s11
	s_nop 0
	global_load_lds_dwordx4 v[172:173], off
	v_lshl_add_u64 v[172:173], v[246:247], 0, s[70:71]
	s_add_i32 m0, s11, 0x2000
	s_nop 0
	global_load_lds_dwordx4 v[172:173], off
	v_lshl_add_u64 v[172:173], v[248:249], 0, s[70:71]
	s_mov_b32 m0, s7
	s_nop 0
	global_load_lds_dwordx4 v[172:173], off
	v_lshl_add_u64 v[172:173], v[250:251], 0, s[70:71]
	s_mov_b32 m0, s6
	s_nop 0
	global_load_lds_dwordx4 v[172:173], off
	s_waitcnt vmcnt(8)
	s_waitcnt lgkmcnt(0)
	s_barrier
	s_waitcnt lgkmcnt(0)
	v_mfma_f32_16x16x32_bf16 v[70:73], v[138:141], v[190:193], v[70:73]
	v_mfma_f32_16x16x32_bf16 v[66:69], v[146:149], v[190:193], v[66:69]
	v_mfma_f32_16x16x32_bf16 v[58:61], v[138:141], v[198:201], v[58:61]
	v_mfma_f32_16x16x32_bf16 v[50:53], v[146:149], v[198:201], v[50:53]
	v_mfma_f32_16x16x32_bf16 v[42:45], v[138:141], v[224:227], v[42:45]
	v_mfma_f32_16x16x32_bf16 v[34:37], v[146:149], v[224:227], v[34:37]
	v_mfma_f32_16x16x32_bf16 v[22:25], v[138:141], v[232:235], v[22:25]
	v_mfma_f32_16x16x32_bf16 v[18:21], v[146:149], v[232:235], v[18:21]
	v_mfma_f32_16x16x32_bf16 v[70:73], v[142:145], v[194:197], v[70:73]
	v_mfma_f32_16x16x32_bf16 v[66:69], v[150:153], v[194:197], v[66:69]
	v_mfma_f32_16x16x32_bf16 v[58:61], v[142:145], v[220:223], v[58:61]
	v_mfma_f32_16x16x32_bf16 v[50:53], v[150:153], v[220:223], v[50:53]
	v_mfma_f32_16x16x32_bf16 v[42:45], v[142:145], v[228:231], v[42:45]
	v_mfma_f32_16x16x32_bf16 v[34:37], v[150:153], v[228:231], v[34:37]
	v_mfma_f32_16x16x32_bf16 v[22:25], v[142:145], v[236:239], v[22:25]
	v_mfma_f32_16x16x32_bf16 v[18:21], v[150:153], v[236:239], v[18:21]
	v_mfma_f32_16x16x32_bf16 v[62:65], v[164:167], v[190:193], v[62:65]
	v_mfma_f32_16x16x32_bf16 v[54:57], v[182:185], v[190:193], v[54:57]
	v_mfma_f32_16x16x32_bf16 v[46:49], v[164:167], v[198:201], v[46:49]
	v_mfma_f32_16x16x32_bf16 v[38:41], v[182:185], v[198:201], v[38:41]
	v_mfma_f32_16x16x32_bf16 v[30:33], v[164:167], v[224:227], v[30:33]
	v_mfma_f32_16x16x32_bf16 v[26:29], v[182:185], v[224:227], v[26:29]
	v_mfma_f32_16x16x32_bf16 v[14:17], v[164:167], v[232:235], v[14:17]
	v_mfma_f32_16x16x32_bf16 v[10:13], v[182:185], v[232:235], v[10:13]
	v_mfma_f32_16x16x32_bf16 v[62:65], v[178:181], v[194:197], v[62:65]
	v_mfma_f32_16x16x32_bf16 v[54:57], v[186:189], v[194:197], v[54:57]
	v_mfma_f32_16x16x32_bf16 v[46:49], v[178:181], v[220:223], v[46:49]
	v_mfma_f32_16x16x32_bf16 v[38:41], v[186:189], v[220:223], v[38:41]
	v_mfma_f32_16x16x32_bf16 v[30:33], v[178:181], v[228:231], v[30:33]
	v_mfma_f32_16x16x32_bf16 v[26:29], v[186:189], v[228:231], v[26:29]
	v_mfma_f32_16x16x32_bf16 v[14:17], v[178:181], v[236:239], v[14:17]
	v_mfma_f32_16x16x32_bf16 v[10:13], v[186:189], v[236:239], v[10:13]
	s_barrier
	s_add_u32 s0, s0, 0x100
	s_addc_u32 s1, s1, 0
	s_add_u32 s3, s3, 0x100
	s_addc_u32 s10, s10, 0
	s_cmp_ge_u32 s26, s95
	s_mov_b32 s11, s26
	s_cbranch_scc0 .LBB0_328
	s_setprio 0
	s_and_b64 vcc, exec, s[18:19]
	s_cbranch_vccz .LBB0_331
	s_barrier
